# attention QK as two back-to-back accumulate chains with K fragments prefetched, unscaled fp8 MFMA form, no-op setprio pairs removed from GEMM loops (on top of SGPR-base DMA, paired MFMAs, DPP stop-bou
# speedup vs baseline: 1.0166x; 1.0040x over previous
.LBB0_216:
	ds_read_b128 v[152:155], v160
	ds_read_b128 v[164:167], v160 offset:1024
	ds_read_b128 v[168:171], v160 offset:2048
	ds_read_b128 v[172:175], v160 offset:3072
	ds_read_b128 v[176:179], v161
	ds_read_b128 v[180:183], v161 offset:1024
	ds_read_b128 v[184:187], v161 offset:2048
	ds_read_b128 v[188:191], v161 offset:3072
	s_add_u32 s20, s0, 0xfff00080
	s_addc_u32 s21, s1, -1
	s_cmp_eq_u32 s30, 60
	s_cselect_b32 s23, s13, s21
	s_cselect_b32 s22, s24, s20
	s_cselect_b32 s21, s15, s29
	s_cselect_b32 s20, s25, s27
	s_add_i32 m0, s39, 0xc000
	ds_read_b128 v[192:195], v162
	ds_read_b128 v[196:199], v162 offset:1024
	ds_read_b128 v[200:203], v162 offset:2048
	ds_read_b128 v[204:207], v162 offset:3072
	ds_read_b128 v[208:211], v162 offset:4096
	ds_read_b128 v[212:215], v162 offset:5120
	ds_read_b128 v[216:219], v162 offset:6144
	ds_read_b128 v[220:223], v162 offset:7168
	global_load_lds_dwordx4 v140, s[0:1]
	s_add_i32 m0, s39, 0xe000
	s_nop 0
	global_load_lds_dwordx4 v142, s[0:1]
	s_waitcnt vmcnt(8)
	s_waitcnt lgkmcnt(0)
	s_barrier
	s_setprio 1
	v_mfma_f32_16x16x32_bf16 v[126:129], v[152:155], v[192:195], v[126:129]
	v_mfma_f32_16x16x32_bf16 v[126:129], v[164:167], v[196:199], v[126:129]
	v_mfma_f32_16x16x32_bf16 v[122:125], v[168:171], v[192:195], v[122:125]
	v_mfma_f32_16x16x32_bf16 v[122:125], v[172:175], v[196:199], v[122:125]
	v_mfma_f32_16x16x32_bf16 v[114:117], v[152:155], v[200:203], v[114:117]
	v_mfma_f32_16x16x32_bf16 v[114:117], v[164:167], v[204:207], v[114:117]
	v_mfma_f32_16x16x32_bf16 v[106:109], v[168:171], v[200:203], v[106:109]
	v_mfma_f32_16x16x32_bf16 v[106:109], v[172:175], v[204:207], v[106:109]
	v_mfma_f32_16x16x32_bf16 v[98:101], v[152:155], v[208:211], v[98:101]
	v_mfma_f32_16x16x32_bf16 v[98:101], v[164:167], v[212:215], v[98:101]
	v_mfma_f32_16x16x32_bf16 v[90:93], v[168:171], v[208:211], v[90:93]
	v_mfma_f32_16x16x32_bf16 v[90:93], v[172:175], v[212:215], v[90:93]
	v_mfma_f32_16x16x32_bf16 v[82:85], v[152:155], v[216:219], v[82:85]
	v_mfma_f32_16x16x32_bf16 v[82:85], v[164:167], v[220:223], v[82:85]
	v_mfma_f32_16x16x32_bf16 v[74:77], v[168:171], v[216:219], v[74:77]
	v_mfma_f32_16x16x32_bf16 v[74:77], v[172:175], v[220:223], v[74:77]
	v_mfma_f32_16x16x32_bf16 v[118:121], v[176:179], v[192:195], v[118:121]
	v_mfma_f32_16x16x32_bf16 v[118:121], v[180:183], v[196:199], v[118:121]
	v_mfma_f32_16x16x32_bf16 v[110:113], v[184:187], v[192:195], v[110:113]
	v_mfma_f32_16x16x32_bf16 v[110:113], v[188:191], v[196:199], v[110:113]
	v_mfma_f32_16x16x32_bf16 v[102:105], v[176:179], v[200:203], v[102:105]
	v_mfma_f32_16x16x32_bf16 v[102:105], v[180:183], v[204:207], v[102:105]
	v_mfma_f32_16x16x32_bf16 v[94:97], v[184:187], v[200:203], v[94:97]
	v_mfma_f32_16x16x32_bf16 v[94:97], v[188:191], v[204:207], v[94:97]
	v_mfma_f32_16x16x32_bf16 v[86:89], v[176:179], v[208:211], v[86:89]
	v_mfma_f32_16x16x32_bf16 v[86:89], v[180:183], v[212:215], v[86:89]
	v_mfma_f32_16x16x32_bf16 v[78:81], v[184:187], v[208:211], v[78:81]
	v_mfma_f32_16x16x32_bf16 v[78:81], v[188:191], v[212:215], v[78:81]
	v_mfma_f32_16x16x32_bf16 v[70:73], v[176:179], v[216:219], v[70:73]
	v_mfma_f32_16x16x32_bf16 v[70:73], v[180:183], v[220:223], v[70:73]
	v_mfma_f32_16x16x32_bf16 v[66:69], v[184:187], v[216:219], v[66:69]
	v_mfma_f32_16x16x32_bf16 v[66:69], v[188:191], v[220:223], v[66:69]
	s_setprio 0
	s_barrier
	s_add_i32 s31, s49, s38
	s_mov_b32 m0, s31
	ds_read_b128 v[192:195], v162 offset:16384
	ds_read_b128 v[196:199], v162 offset:17408
	ds_read_b128 v[200:203], v162 offset:18432
	ds_read_b128 v[204:207], v162 offset:19456
	ds_read_b128 v[208:211], v162 offset:20480
	ds_read_b128 v[212:215], v162 offset:21504
	ds_read_b128 v[216:219], v162 offset:22528
	ds_read_b128 v[220:223], v162 offset:23552
	global_load_lds_dwordx4 v132, s[20:21]
	s_add_i32 m0, s31, 0x2000
	s_add_u32 s34, s20, 0x100000
	s_addc_u32 s35, s21, 0
	s_add_i32 s31, s50, s38
	global_load_lds_dwordx4 v136, s[20:21]
	s_mov_b32 m0, s31
	global_load_lds_dwordx4 v132, s[34:35]
	s_add_i32 m0, s31, 0x2000
	s_nop 0
	global_load_lds_dwordx4 v136, s[34:35]
	s_mov_b32 m0, s39
	s_nop 0
	global_load_lds_dwordx4 v130, s[22:23]
	s_mov_b32 m0, s40
	s_nop 0
	global_load_lds_dwordx4 v134, s[22:23]
	s_waitcnt vmcnt(8)
	s_waitcnt lgkmcnt(0)
	s_barrier
	s_setprio 1
	v_mfma_f32_16x16x32_bf16 v[62:65], v[152:155], v[192:195], v[62:65]
	v_mfma_f32_16x16x32_bf16 v[62:65], v[164:167], v[196:199], v[62:65]
	v_mfma_f32_16x16x32_bf16 v[58:61], v[168:171], v[192:195], v[58:61]
	v_mfma_f32_16x16x32_bf16 v[58:61], v[172:175], v[196:199], v[58:61]
	v_mfma_f32_16x16x32_bf16 v[46:49], v[152:155], v[200:203], v[46:49]
	v_mfma_f32_16x16x32_bf16 v[46:49], v[164:167], v[204:207], v[46:49]
	v_mfma_f32_16x16x32_bf16 v[42:45], v[168:171], v[200:203], v[42:45]
	v_mfma_f32_16x16x32_bf16 v[42:45], v[172:175], v[204:207], v[42:45]
	v_mfma_f32_16x16x32_bf16 v[30:33], v[152:155], v[208:211], v[30:33]
	v_mfma_f32_16x16x32_bf16 v[30:33], v[164:167], v[212:215], v[30:33]
	v_mfma_f32_16x16x32_bf16 v[26:29], v[168:171], v[208:211], v[26:29]
	v_mfma_f32_16x16x32_bf16 v[26:29], v[172:175], v[212:215], v[26:29]
	v_mfma_f32_16x16x32_bf16 v[14:17], v[152:155], v[216:219], v[14:17]
	v_mfma_f32_16x16x32_bf16 v[14:17], v[164:167], v[220:223], v[14:17]
	v_mfma_f32_16x16x32_bf16 v[10:13], v[168:171], v[216:219], v[10:13]
	v_mfma_f32_16x16x32_bf16 v[10:13], v[172:175], v[220:223], v[10:13]
	v_mfma_f32_16x16x32_bf16 v[54:57], v[176:179], v[192:195], v[54:57]
	v_mfma_f32_16x16x32_bf16 v[54:57], v[180:183], v[196:199], v[54:57]
	v_mfma_f32_16x16x32_bf16 v[50:53], v[184:187], v[192:195], v[50:53]
	v_mfma_f32_16x16x32_bf16 v[50:53], v[188:191], v[196:199], v[50:53]
	v_mfma_f32_16x16x32_bf16 v[38:41], v[176:179], v[200:203], v[38:41]
	v_mfma_f32_16x16x32_bf16 v[38:41], v[180:183], v[204:207], v[38:41]
	v_mfma_f32_16x16x32_bf16 v[34:37], v[184:187], v[200:203], v[34:37]
	v_mfma_f32_16x16x32_bf16 v[34:37], v[188:191], v[204:207], v[34:37]
	v_mfma_f32_16x16x32_bf16 v[22:25], v[176:179], v[208:211], v[22:25]
	v_mfma_f32_16x16x32_bf16 v[22:25], v[180:183], v[212:215], v[22:25]
	v_mfma_f32_16x16x32_bf16 v[18:21], v[184:187], v[208:211], v[18:21]
	v_mfma_f32_16x16x32_bf16 v[18:21], v[188:191], v[212:215], v[18:21]
	v_mfma_f32_16x16x32_bf16 v[6:9], v[176:179], v[216:219], v[6:9]
	v_mfma_f32_16x16x32_bf16 v[6:9], v[180:183], v[220:223], v[6:9]
	v_mfma_f32_16x16x32_bf16 v[2:5], v[184:187], v[216:219], v[2:5]
	v_mfma_f32_16x16x32_bf16 v[2:5], v[188:191], v[220:223], v[2:5]
	s_setprio 0
	s_barrier
	s_add_i32 s31, 0, 0x18000
	v_add_u32_e32 v138, s31, v158
	s_add_i32 s33, 0, 0x1c000
	ds_read_b128 v[152:155], v138
	ds_read_b128 v[164:167], v138 offset:1024
	ds_read_b128 v[168:171], v138 offset:2048
	ds_read_b128 v[172:175], v138 offset:3072
	v_add_u32_e32 v138, s33, v158
	ds_read_b128 v[176:179], v138
	ds_read_b128 v[180:183], v138 offset:1024
	ds_read_b128 v[184:187], v138 offset:2048
	ds_read_b128 v[188:191], v138 offset:3072
	s_add_u32 s98, s22, 0x80
	s_addc_u32 s99, s23, 0
	s_add_u32 s22, s22, 0x100000
	s_addc_u32 s23, s23, 0
	s_mov_b32 m0, s41
	ds_read_b128 v[192:195], v162 offset:32768
	ds_read_b128 v[196:199], v162 offset:33792
	ds_read_b128 v[200:203], v162 offset:34816
	ds_read_b128 v[204:207], v162 offset:35840
	ds_read_b128 v[208:211], v162 offset:36864
	ds_read_b128 v[212:215], v162 offset:37888
	ds_read_b128 v[216:219], v162 offset:38912
	ds_read_b128 v[220:223], v162 offset:39936
	global_load_lds_dwordx4 v130, s[22:23]
	s_mov_b32 m0, s42
	s_nop 0
	global_load_lds_dwordx4 v134, s[22:23]
	s_waitcnt vmcnt(8)
	s_waitcnt lgkmcnt(0)
	s_barrier
	s_setprio 1
	v_mfma_f32_16x16x32_bf16 v[126:129], v[152:155], v[192:195], v[126:129]
	v_mfma_f32_16x16x32_bf16 v[126:129], v[164:167], v[196:199], v[126:129]
	v_mfma_f32_16x16x32_bf16 v[122:125], v[168:171], v[192:195], v[122:125]
	v_mfma_f32_16x16x32_bf16 v[122:125], v[172:175], v[196:199], v[122:125]
	v_mfma_f32_16x16x32_bf16 v[114:117], v[152:155], v[200:203], v[114:117]
	v_mfma_f32_16x16x32_bf16 v[114:117], v[164:167], v[204:207], v[114:117]
	v_mfma_f32_16x16x32_bf16 v[106:109], v[168:171], v[200:203], v[106:109]
	v_mfma_f32_16x16x32_bf16 v[106:109], v[172:175], v[204:207], v[106:109]
	v_mfma_f32_16x16x32_bf16 v[98:101], v[152:155], v[208:211], v[98:101]
	v_mfma_f32_16x16x32_bf16 v[98:101], v[164:167], v[212:215], v[98:101]
	v_mfma_f32_16x16x32_bf16 v[90:93], v[168:171], v[208:211], v[90:93]
	v_mfma_f32_16x16x32_bf16 v[90:93], v[172:175], v[212:215], v[90:93]
	v_mfma_f32_16x16x32_bf16 v[82:85], v[152:155], v[216:219], v[82:85]
	v_mfma_f32_16x16x32_bf16 v[82:85], v[164:167], v[220:223], v[82:85]
	v_mfma_f32_16x16x32_bf16 v[74:77], v[168:171], v[216:219], v[74:77]
	v_mfma_f32_16x16x32_bf16 v[74:77], v[172:175], v[220:223], v[74:77]
	v_mfma_f32_16x16x32_bf16 v[118:121], v[176:179], v[192:195], v[118:121]
	v_mfma_f32_16x16x32_bf16 v[118:121], v[180:183], v[196:199], v[118:121]
	v_mfma_f32_16x16x32_bf16 v[110:113], v[184:187], v[192:195], v[110:113]
	v_mfma_f32_16x16x32_bf16 v[110:113], v[188:191], v[196:199], v[110:113]
	v_mfma_f32_16x16x32_bf16 v[102:105], v[176:179], v[200:203], v[102:105]
	v_mfma_f32_16x16x32_bf16 v[102:105], v[180:183], v[204:207], v[102:105]
	v_mfma_f32_16x16x32_bf16 v[94:97], v[184:187], v[200:203], v[94:97]
	v_mfma_f32_16x16x32_bf16 v[94:97], v[188:191], v[204:207], v[94:97]
	v_mfma_f32_16x16x32_bf16 v[86:89], v[176:179], v[208:211], v[86:89]
	v_mfma_f32_16x16x32_bf16 v[86:89], v[180:183], v[212:215], v[86:89]
	v_mfma_f32_16x16x32_bf16 v[78:81], v[184:187], v[208:211], v[78:81]
	v_mfma_f32_16x16x32_bf16 v[78:81], v[188:191], v[212:215], v[78:81]
	v_mfma_f32_16x16x32_bf16 v[70:73], v[176:179], v[216:219], v[70:73]
	v_mfma_f32_16x16x32_bf16 v[70:73], v[180:183], v[220:223], v[70:73]
	v_mfma_f32_16x16x32_bf16 v[66:69], v[184:187], v[216:219], v[66:69]
	v_mfma_f32_16x16x32_bf16 v[66:69], v[188:191], v[220:223], v[66:69]
	s_setprio 0
	s_barrier
	s_add_i32 s22, s31, s38
	s_mov_b32 m0, s22
	ds_read_b128 v[192:195], v162 offset:49152
	ds_read_b128 v[196:199], v162 offset:50176
	ds_read_b128 v[200:203], v162 offset:51200
	ds_read_b128 v[204:207], v162 offset:52224
	ds_read_b128 v[208:211], v162 offset:53248
	ds_read_b128 v[212:215], v162 offset:54272
	ds_read_b128 v[216:219], v162 offset:55296
	ds_read_b128 v[220:223], v162 offset:56320
	s_add_u32 s20, s20, 0x80
	s_addc_u32 s21, s21, 0
	global_load_lds_dwordx4 v132, s[20:21]
	s_add_i32 m0, s22, 0x2000
	s_add_i32 s22, s33, s38
	global_load_lds_dwordx4 v136, s[20:21]
	s_add_u32 s20, s20, 0x100000
	s_addc_u32 s21, s21, 0
	s_mov_b32 m0, s22
	s_nop 0
	global_load_lds_dwordx4 v132, s[20:21]
	s_add_i32 m0, s22, 0x2000
	s_nop 0
	global_load_lds_dwordx4 v136, s[20:21]
	s_mov_b32 m0, s45
	s_nop 0
	global_load_lds_dwordx4 v130, s[98:99]
	s_mov_b32 m0, s46
	s_nop 0
	global_load_lds_dwordx4 v134, s[98:99]
	s_waitcnt vmcnt(8)
	s_waitcnt lgkmcnt(0)
	s_barrier
	s_setprio 1
	v_mfma_f32_16x16x32_bf16 v[62:65], v[152:155], v[192:195], v[62:65]
	v_mfma_f32_16x16x32_bf16 v[62:65], v[164:167], v[196:199], v[62:65]
	v_mfma_f32_16x16x32_bf16 v[58:61], v[168:171], v[192:195], v[58:61]
	v_mfma_f32_16x16x32_bf16 v[58:61], v[172:175], v[196:199], v[58:61]
	v_mfma_f32_16x16x32_bf16 v[46:49], v[152:155], v[200:203], v[46:49]
	v_mfma_f32_16x16x32_bf16 v[46:49], v[164:167], v[204:207], v[46:49]
	v_mfma_f32_16x16x32_bf16 v[42:45], v[168:171], v[200:203], v[42:45]
	v_mfma_f32_16x16x32_bf16 v[42:45], v[172:175], v[204:207], v[42:45]
	v_mfma_f32_16x16x32_bf16 v[30:33], v[152:155], v[208:211], v[30:33]
	v_mfma_f32_16x16x32_bf16 v[30:33], v[164:167], v[212:215], v[30:33]
	v_mfma_f32_16x16x32_bf16 v[26:29], v[168:171], v[208:211], v[26:29]
	v_mfma_f32_16x16x32_bf16 v[26:29], v[172:175], v[212:215], v[26:29]
	v_mfma_f32_16x16x32_bf16 v[14:17], v[152:155], v[216:219], v[14:17]
	v_mfma_f32_16x16x32_bf16 v[14:17], v[164:167], v[220:223], v[14:17]
	v_mfma_f32_16x16x32_bf16 v[10:13], v[168:171], v[216:219], v[10:13]
	v_mfma_f32_16x16x32_bf16 v[10:13], v[172:175], v[220:223], v[10:13]
	v_mfma_f32_16x16x32_bf16 v[54:57], v[176:179], v[192:195], v[54:57]
	v_mfma_f32_16x16x32_bf16 v[54:57], v[180:183], v[196:199], v[54:57]
	v_mfma_f32_16x16x32_bf16 v[50:53], v[184:187], v[192:195], v[50:53]
	v_mfma_f32_16x16x32_bf16 v[50:53], v[188:191], v[196:199], v[50:53]
	v_mfma_f32_16x16x32_bf16 v[38:41], v[176:179], v[200:203], v[38:41]
	v_mfma_f32_16x16x32_bf16 v[38:41], v[180:183], v[204:207], v[38:41]
	v_mfma_f32_16x16x32_bf16 v[34:37], v[184:187], v[200:203], v[34:37]
	v_mfma_f32_16x16x32_bf16 v[34:37], v[188:191], v[204:207], v[34:37]
	v_mfma_f32_16x16x32_bf16 v[22:25], v[176:179], v[208:211], v[22:25]
	v_mfma_f32_16x16x32_bf16 v[22:25], v[180:183], v[212:215], v[22:25]
	v_mfma_f32_16x16x32_bf16 v[18:21], v[184:187], v[208:211], v[18:21]
	v_mfma_f32_16x16x32_bf16 v[18:21], v[188:191], v[212:215], v[18:21]
	v_mfma_f32_16x16x32_bf16 v[6:9], v[176:179], v[216:219], v[6:9]
	v_mfma_f32_16x16x32_bf16 v[6:9], v[180:183], v[220:223], v[6:9]
	v_mfma_f32_16x16x32_bf16 v[2:5], v[184:187], v[216:219], v[2:5]
	v_mfma_f32_16x16x32_bf16 v[2:5], v[188:191], v[220:223], v[2:5]
	s_setprio 0
	s_barrier
	s_add_i32 s30, s30, 2
	s_add_u32 s0, s0, 0x100
	s_addc_u32 s1, s1, 0
	s_add_u32 s27, s27, 0x100
	s_addc_u32 s29, s29, 0
	s_cmp_gt_u32 s30, 61
	s_cbranch_scc0 .LBB0_216
	s_and_b64 vcc, exec, s[10:11]
	s_cbranch_vccz .LBB0_219
	s_barrier

.LBB0_271:
	ds_read_b128 v[26:29], v183
	ds_read_b128 v[30:33], v183 offset:16
	ds_read_b128 v[18:21], v183 offset:2048
	ds_read_b128 v[22:25], v183 offset:2064
	ds_read_b128 v[10:13], v184
	ds_read_b128 v[14:17], v184 offset:16
	ds_read_b128 v[2:5], v184 offset:2048
	ds_read_b128 v[6:9], v184 offset:2064
	s_add_u32 s0, s20, 0xfff80080
	s_addc_u32 s1, s21, -1
	s_cmp_eq_u32 s29, 28
	s_cselect_b32 s23, s13, s1
	s_cselect_b32 s22, s25, s0
	s_cselect_b32 s1, s11, s28
	s_cselect_b32 s0, s26, s27
	s_add_i32 m0, s19, 0xc000
	ds_read_b128 v[174:177], v185
	ds_read_b128 v[178:181], v185 offset:16
	ds_read_b128 v[188:191], v185 offset:2048
	ds_read_b128 v[192:195], v185 offset:2064
	ds_read_b128 v[196:199], v185 offset:4096
	ds_read_b128 v[200:203], v185 offset:4112
	ds_read_b128 v[204:207], v185 offset:6144
	ds_read_b128 v[208:211], v185 offset:6160
	global_load_lds_dwordx4 v162, s[20:21]
	s_add_i32 m0, s19, 0xe000
	s_nop 0
	global_load_lds_dwordx4 v172, s[20:21]
	s_waitcnt vmcnt(8)
	s_waitcnt lgkmcnt(0)
	s_barrier
	s_setprio 1
	v_mfma_f32_16x16x128_f8f6f4 v[158:161], v[26:33], v[174:181], v[158:161]
	v_mfma_f32_16x16x128_f8f6f4 v[154:157], v[18:25], v[174:181], v[154:157]
	v_mfma_f32_16x16x128_f8f6f4 v[146:149], v[26:33], v[188:195], v[146:149]
	v_mfma_f32_16x16x128_f8f6f4 v[138:141], v[18:25], v[188:195], v[138:141]
	v_mfma_f32_16x16x128_f8f6f4 v[130:133], v[26:33], v[196:203], v[130:133]
	v_mfma_f32_16x16x128_f8f6f4 v[122:125], v[18:25], v[196:203], v[122:125]
	v_mfma_f32_16x16x128_f8f6f4 v[114:117], v[26:33], v[204:211], v[114:117]
	v_mfma_f32_16x16x128_f8f6f4 v[106:109], v[18:25], v[204:211], v[106:109]
	v_mfma_f32_16x16x128_f8f6f4 v[150:153], v[10:17], v[174:181], v[150:153]
	v_mfma_f32_16x16x128_f8f6f4 v[142:145], v[2:9], v[174:181], v[142:145]
	v_mfma_f32_16x16x128_f8f6f4 v[134:137], v[10:17], v[188:195], v[134:137]
	v_mfma_f32_16x16x128_f8f6f4 v[126:129], v[2:9], v[188:195], v[126:129]
	v_mfma_f32_16x16x128_f8f6f4 v[118:121], v[10:17], v[196:203], v[118:121]
	v_mfma_f32_16x16x128_f8f6f4 v[110:113], v[2:9], v[196:203], v[110:113]
	v_mfma_f32_16x16x128_f8f6f4 v[102:105], v[10:17], v[204:211], v[102:105]
	v_mfma_f32_16x16x128_f8f6f4 v[98:101], v[2:9], v[204:211], v[98:101]
	s_setprio 0
	s_barrier
	s_add_i32 s30, s48, s37
	s_mov_b32 m0, s30
	ds_read_b128 v[188:191], v185 offset:16384
	ds_read_b128 v[192:195], v185 offset:16400
	ds_read_b128 v[196:199], v185 offset:18432
	ds_read_b128 v[200:203], v185 offset:18448
	ds_read_b128 v[204:207], v185 offset:20480
	ds_read_b128 v[208:211], v185 offset:20496
	ds_read_b128 v[212:215], v185 offset:22528
	ds_read_b128 v[216:219], v185 offset:22544
	global_load_lds_dwordx4 v168, s[0:1]
	s_add_i32 m0, s30, 0x2000
	s_add_u32 s30, s0, 0x80000
	s_addc_u32 s31, s1, 0
	s_add_i32 s33, s49, s37
	global_load_lds_dwordx4 v170, s[0:1]
	s_mov_b32 m0, s33
	global_load_lds_dwordx4 v168, s[30:31]
	s_add_i32 m0, s33, 0x2000
	s_nop 0
	global_load_lds_dwordx4 v170, s[30:31]
	s_mov_b32 m0, s19
	s_nop 0
	global_load_lds_dwordx4 v162, s[22:23]
	s_mov_b32 m0, s38
	s_nop 0
	global_load_lds_dwordx4 v172, s[22:23]
	s_waitcnt vmcnt(8)
	s_waitcnt lgkmcnt(0)
	s_barrier
	s_setprio 1
	v_mfma_f32_16x16x128_f8f6f4 v[94:97], v[26:33], v[188:195], v[94:97]
	v_mfma_f32_16x16x128_f8f6f4 v[90:93], v[18:25], v[188:195], v[90:93]
	v_mfma_f32_16x16x128_f8f6f4 v[78:81], v[26:33], v[196:203], v[78:81]
	v_mfma_f32_16x16x128_f8f6f4 v[74:77], v[18:25], v[196:203], v[74:77]
	v_mfma_f32_16x16x128_f8f6f4 v[62:65], v[26:33], v[204:211], v[62:65]
	v_mfma_f32_16x16x128_f8f6f4 v[58:61], v[18:25], v[204:211], v[58:61]
	v_mfma_f32_16x16x128_f8f6f4 v[46:49], v[26:33], v[212:219], v[46:49]
	v_mfma_f32_16x16x128_f8f6f4 v[42:45], v[18:25], v[212:219], v[42:45]
	v_mfma_f32_16x16x128_f8f6f4 v[86:89], v[10:17], v[188:195], v[86:89]
	v_mfma_f32_16x16x128_f8f6f4 v[82:85], v[2:9], v[188:195], v[82:85]
	v_mfma_f32_16x16x128_f8f6f4 v[70:73], v[10:17], v[196:203], v[70:73]
	v_mfma_f32_16x16x128_f8f6f4 v[66:69], v[2:9], v[196:203], v[66:69]
	v_mfma_f32_16x16x128_f8f6f4 v[54:57], v[10:17], v[204:211], v[54:57]
	v_mfma_f32_16x16x128_f8f6f4 v[50:53], v[2:9], v[204:211], v[50:53]
	v_mfma_f32_16x16x128_f8f6f4 v[38:41], v[10:17], v[212:219], v[38:41]
	v_mfma_f32_16x16x128_f8f6f4 v[34:37], v[2:9], v[212:219], v[34:37]
	s_setprio 0
	s_barrier
	s_add_i32 s30, 0, 0x18000
	s_add_i32 s31, 0, 0x1c000
	v_add_u32_e32 v14, s30, v182
	v_add_u32_e32 v30, s31, v182
	ds_read_b128 v[2:5], v14
	ds_read_b128 v[6:9], v14 offset:16
	ds_read_b128 v[10:13], v14 offset:2048
	ds_read_b128 v[14:17], v14 offset:2064
	ds_read_b128 v[18:21], v30
	ds_read_b128 v[22:25], v30 offset:16
	ds_read_b128 v[26:29], v30 offset:2048
	ds_read_b128 v[30:33], v30 offset:2064
	s_add_u32 s98, s22, 0x80
	s_addc_u32 s99, s23, 0
	s_add_u32 s22, s22, 0x80000
	s_addc_u32 s23, s23, 0
	s_mov_b32 m0, s39
	ds_read_b128 v[188:191], v185 offset:32768
	ds_read_b128 v[192:195], v185 offset:32784
	ds_read_b128 v[196:199], v185 offset:34816
	ds_read_b128 v[200:203], v185 offset:34832
	ds_read_b128 v[204:207], v185 offset:36864
	ds_read_b128 v[208:211], v185 offset:36880
	ds_read_b128 v[212:215], v185 offset:38912
	ds_read_b128 v[216:219], v185 offset:38928
	global_load_lds_dwordx4 v162, s[22:23]
	s_mov_b32 m0, s40
	s_nop 0
	global_load_lds_dwordx4 v172, s[22:23]
	s_waitcnt vmcnt(8)
	s_waitcnt lgkmcnt(0)
	s_barrier
	s_setprio 1
	v_mfma_f32_16x16x128_f8f6f4 v[158:161], v[2:9], v[188:195], v[158:161]
	v_mfma_f32_16x16x128_f8f6f4 v[154:157], v[10:17], v[188:195], v[154:157]
	v_mfma_f32_16x16x128_f8f6f4 v[146:149], v[2:9], v[196:203], v[146:149]
	v_mfma_f32_16x16x128_f8f6f4 v[138:141], v[10:17], v[196:203], v[138:141]
	v_mfma_f32_16x16x128_f8f6f4 v[130:133], v[2:9], v[204:211], v[130:133]
	v_mfma_f32_16x16x128_f8f6f4 v[122:125], v[10:17], v[204:211], v[122:125]
	v_mfma_f32_16x16x128_f8f6f4 v[114:117], v[2:9], v[212:219], v[114:117]
	v_mfma_f32_16x16x128_f8f6f4 v[106:109], v[10:17], v[212:219], v[106:109]
	v_mfma_f32_16x16x128_f8f6f4 v[150:153], v[18:25], v[188:195], v[150:153]
	v_mfma_f32_16x16x128_f8f6f4 v[142:145], v[26:33], v[188:195], v[142:145]
	v_mfma_f32_16x16x128_f8f6f4 v[134:137], v[18:25], v[196:203], v[134:137]
	v_mfma_f32_16x16x128_f8f6f4 v[126:129], v[26:33], v[196:203], v[126:129]
	v_mfma_f32_16x16x128_f8f6f4 v[118:121], v[18:25], v[204:211], v[118:121]
	v_mfma_f32_16x16x128_f8f6f4 v[110:113], v[26:33], v[204:211], v[110:113]
	v_mfma_f32_16x16x128_f8f6f4 v[102:105], v[18:25], v[212:219], v[102:105]
	v_mfma_f32_16x16x128_f8f6f4 v[98:101], v[26:33], v[212:219], v[98:101]
	s_setprio 0
	s_barrier
	s_add_i32 s22, s30, s37
	s_mov_b32 m0, s22
	ds_read_b128 v[188:191], v185 offset:49152
	ds_read_b128 v[192:195], v185 offset:49168
	ds_read_b128 v[196:199], v185 offset:51200
	ds_read_b128 v[200:203], v185 offset:51216
	ds_read_b128 v[204:207], v185 offset:53248
	ds_read_b128 v[208:211], v185 offset:53264
	ds_read_b128 v[212:215], v185 offset:55296
	ds_read_b128 v[216:219], v185 offset:55312
	s_add_u32 s0, s0, 0x80
	s_addc_u32 s1, s1, 0
	global_load_lds_dwordx4 v168, s[0:1]
	s_add_i32 m0, s22, 0x2000
	s_add_i32 s22, s31, s37
	global_load_lds_dwordx4 v170, s[0:1]
	s_add_u32 s0, s0, 0x80000
	s_addc_u32 s1, s1, 0
	s_mov_b32 m0, s22
	s_nop 0
	global_load_lds_dwordx4 v168, s[0:1]
	s_add_i32 m0, s22, 0x2000
	s_nop 0
	global_load_lds_dwordx4 v170, s[0:1]
	s_mov_b32 m0, s44
	s_nop 0
	global_load_lds_dwordx4 v162, s[98:99]
	s_mov_b32 m0, s45
	s_nop 0
	global_load_lds_dwordx4 v172, s[98:99]
	s_waitcnt vmcnt(8)
	s_waitcnt lgkmcnt(0)
	s_barrier
	s_setprio 1
	v_mfma_f32_16x16x128_f8f6f4 v[94:97], v[2:9], v[188:195], v[94:97]
	v_mfma_f32_16x16x128_f8f6f4 v[90:93], v[10:17], v[188:195], v[90:93]
	v_mfma_f32_16x16x128_f8f6f4 v[78:81], v[2:9], v[196:203], v[78:81]
	v_mfma_f32_16x16x128_f8f6f4 v[74:77], v[10:17], v[196:203], v[74:77]
	v_mfma_f32_16x16x128_f8f6f4 v[62:65], v[2:9], v[204:211], v[62:65]
	v_mfma_f32_16x16x128_f8f6f4 v[58:61], v[10:17], v[204:211], v[58:61]
	v_mfma_f32_16x16x128_f8f6f4 v[46:49], v[2:9], v[212:219], v[46:49]
	v_mfma_f32_16x16x128_f8f6f4 v[42:45], v[10:17], v[212:219], v[42:45]
	v_mfma_f32_16x16x128_f8f6f4 v[86:89], v[18:25], v[188:195], v[86:89]
	v_mfma_f32_16x16x128_f8f6f4 v[82:85], v[26:33], v[188:195], v[82:85]
	v_mfma_f32_16x16x128_f8f6f4 v[70:73], v[18:25], v[196:203], v[70:73]
	v_mfma_f32_16x16x128_f8f6f4 v[66:69], v[26:33], v[196:203], v[66:69]
	v_mfma_f32_16x16x128_f8f6f4 v[54:57], v[18:25], v[204:211], v[54:57]
	v_mfma_f32_16x16x128_f8f6f4 v[50:53], v[26:33], v[204:211], v[50:53]
	v_mfma_f32_16x16x128_f8f6f4 v[38:41], v[18:25], v[212:219], v[38:41]
	v_mfma_f32_16x16x128_f8f6f4 v[34:37], v[26:33], v[212:219], v[34:37]
	s_setprio 0
	s_barrier
	s_add_i32 s29, s29, 2
	s_add_u32 s20, s20, 0x100
	s_addc_u32 s21, s21, 0
	s_add_u32 s27, s27, 0x100
	s_addc_u32 s28, s28, 0
	s_cmp_gt_u32 s29, 29
	s_cbranch_scc0 .LBB0_271
	s_and_b64 vcc, exec, s[8:9]
	s_cbranch_vccz .LBB0_274
	s_barrier

.LBB0_572:
	s_add_i32 s9, s9, 3
	s_waitcnt lgkmcnt(0)
	v_lshl_add_u32 v157, s81, 13, v132
	s_cmp_lt_u32 s83, 4
	ds_read_b128 v[192:195], v157
	ds_read_b128 v[200:203], v157 offset:2048
	ds_read_b128 v[208:211], v157 offset:4096
	ds_read_b128 v[220:223], v157 offset:6144
	ds_read_b128 v[196:199], v157 offset:512
	ds_read_b128 v[204:207], v157 offset:2560
	ds_read_b128 v[212:215], v157 offset:4608
	ds_read_b128 v[228:231], v157 offset:6656
	s_cselect_b32 s8, s8, s9
	v_lshl_add_u32 v156, s8, 6, v151
	v_cvt_f32_i32_e32 v66, v156
	s_cmp_lt_i32 s8, s84
	v_fma_f32 v81, v117, v66, -v155
	v_add_f32_e32 v97, v149, v81
	v_add_f32 v66, v133, v81
	v_add_f32 v67, v117, v81
	v_add_f32 v68, v134, v81
	v_add_f32 v69, v135, v81
	v_add_f32 v70, v136, v81
	v_add_f32 v71, v137, v81
	v_add_f32 v72, v138, v81
	v_add_f32 v73, v139, v81
	v_add_f32 v74, v140, v81
	v_add_f32 v75, v141, v81
	v_add_f32 v76, v142, v81
	v_add_f32 v77, v143, v81
	v_add_f32 v78, v144, v81
	v_add_f32 v79, v145, v81
	v_add_f32 v80, v146, v81
	v_add_f32 v81, v148, v81
	v_add_f32 v82, v133, v97
	v_add_f32 v83, v117, v97
	v_add_f32 v84, v134, v97
	v_add_f32 v85, v135, v97
	v_add_f32 v86, v136, v97
	v_add_f32 v87, v137, v97
	v_add_f32 v88, v138, v97
	v_add_f32 v89, v139, v97
	v_add_f32 v90, v140, v97
	s_waitcnt lgkmcnt(4)
	v_mfma_f32_32x32x16_bf16 v[66:81], v[192:195], v[98:101], v[66:81]
	v_mfma_f32_32x32x16_bf16 v[66:81], v[200:203], v[102:105], v[66:81]
	v_mfma_f32_32x32x16_bf16 v[66:81], v[208:211], v[106:109], v[66:81]
	v_mfma_f32_32x32x16_bf16 v[66:81], v[220:223], v[110:113], v[66:81]
	v_add_f32 v91, v141, v97
	v_add_f32 v92, v142, v97
	v_add_f32 v93, v143, v97
	v_add_f32 v94, v144, v97
	v_add_f32 v95, v145, v97
	v_add_f32 v96, v146, v97
	v_add_f32 v97, v148, v97
	s_waitcnt lgkmcnt(0)
	s_nop 1
	v_mfma_f32_32x32x16_bf16 v[82:97], v[196:199], v[98:101], v[82:97]
	v_mfma_f32_32x32x16_bf16 v[82:97], v[204:207], v[102:105], v[82:97]
	v_mfma_f32_32x32x16_bf16 v[82:97], v[212:215], v[106:109], v[82:97]
	v_mfma_f32_32x32x16_bf16 v[82:97], v[228:231], v[110:113], v[82:97]
	s_cbranch_scc1 .LBB0_574
	s_movk_i32 s36, 0xffe6
	s_movk_i32 s64, 0xffe5
	s_movk_i32 s34, 0xffe7
	v_cmp_lt_i32_e64 s[62:63], s36, v156
	v_cmp_lt_i32_e64 s[64:65], s64, v156
	s_movk_i32 s30, 0xffe8
	v_cmp_lt_i32_e64 s[60:61], s34, v156
	s_and_b64 s[62:63], s[64:65], s[62:63]
	s_movk_i32 s28, 0xffed
	v_cmp_lt_i32_e64 s[58:59], s30, v156
	s_and_b64 s[60:61], s[62:63], s[60:61]
	s_movk_i32 s26, 0xffee
	v_cmp_lt_i32_e64 s[56:57], s28, v156
	s_and_b64 s[58:59], s[60:61], s[58:59]
	s_movk_i32 s24, 0xffef
	v_cmp_lt_i32_e64 s[54:55], s26, v156
	s_and_b64 s[56:57], s[58:59], s[56:57]
	v_cmp_lt_i32_e64 s[52:53], s24, v156
	s_and_b64 s[54:55], s[56:57], s[54:55]
	v_cmp_lt_i32_e64 s[50:51], -16, v156
	s_and_b64 s[52:53], s[54:55], s[52:53]
	v_cmp_lt_i32_e64 s[48:49], -11, v156
	s_and_b64 s[50:51], s[52:53], s[50:51]
	v_cmp_lt_i32_e64 s[46:47], -10, v156
	s_and_b64 s[48:49], s[50:51], s[48:49]
	v_cmp_lt_i32_e64 s[44:45], -9, v156
	s_and_b64 s[46:47], s[48:49], s[46:47]
	s_movk_i32 s10, 0xffe0
	v_cmp_lt_i32_e64 s[42:43], -8, v156
	s_and_b64 s[44:45], s[46:47], s[44:45]
	v_cmp_gt_i32_e64 s[8:9], 1, v156
	v_cmp_lt_i32_e32 vcc, s10, v156
	v_cmp_gt_i32_e64 s[10:11], 0, v156
	v_cmp_lt_i32_e64 s[40:41], -3, v156
	s_and_b64 s[42:43], s[44:45], s[42:43]
	s_or_b64 s[8:9], s[10:11], s[8:9]
	v_cmp_lt_i32_e64 s[38:39], -2, v156
	s_and_b64 s[40:41], s[42:43], s[40:41]
	v_cndmask_b32_e64 v157, v127, v67, s[10:11]
	v_cndmask_b32_e64 v158, v127, v66, s[8:9]
	s_and_b64 s[38:39], s[40:41], s[38:39]
	s_movk_i32 s36, 0xffc6
	v_cndmask_b32_e64 v66, v66, v158, s[38:39]
	v_cndmask_b32_e64 v68, v68, v127, s[38:39]
	v_cndmask_b32_e64 v67, v67, v157, s[38:39]
	s_movk_i32 s38, 0xffc5
	s_movk_i32 s34, 0xffc7
	v_cmp_lt_i32_e64 s[36:37], s36, v156
	v_cmp_lt_i32_e64 s[38:39], s38, v156
	s_movk_i32 s30, 0xffc8
	v_cmp_lt_i32_e64 s[34:35], s34, v156
	s_and_b64 s[36:37], s[38:39], s[36:37]
	s_movk_i32 s28, 0xffcd
	v_cmp_lt_i32_e64 s[30:31], s30, v156
	s_and_b64 s[34:35], s[36:37], s[34:35]
	s_movk_i32 s26, 0xffce
	v_cmp_lt_i32_e64 s[28:29], s28, v156
	s_and_b64 s[30:31], s[34:35], s[30:31]
	s_movk_i32 s24, 0xffcf
	v_cmp_lt_i32_e64 s[26:27], s26, v156
	s_and_b64 s[28:29], s[30:31], s[28:29]
	s_movk_i32 s22, 0xffd0
	v_cmp_lt_i32_e64 s[24:25], s24, v156
	s_and_b64 s[26:27], s[28:29], s[26:27]
	s_movk_i32 s20, 0xffd5
	v_cmp_lt_i32_e64 s[22:23], s22, v156
	s_and_b64 s[24:25], s[26:27], s[24:25]
	s_movk_i32 s18, 0xffd6
	v_cmp_lt_i32_e64 s[20:21], s20, v156
	s_and_b64 s[22:23], s[24:25], s[22:23]
	s_movk_i32 s16, 0xffd7
	v_cmp_lt_i32_e64 s[18:19], s18, v156
	s_and_b64 s[20:21], s[22:23], s[20:21]
	s_movk_i32 s14, 0xffd8
	v_cmp_lt_i32_e64 s[16:17], s16, v156
	s_and_b64 s[18:19], s[20:21], s[18:19]
	s_movk_i32 s12, 0xffdd
	v_cmp_lt_i32_e64 s[14:15], s14, v156
	s_and_b64 s[16:17], s[18:19], s[16:17]
	s_movk_i32 s10, 0xffde
	v_cmp_lt_i32_e64 s[12:13], s12, v156
	s_and_b64 s[14:15], s[16:17], s[14:15]
	s_movk_i32 s8, 0xffdf
	v_cmp_lt_i32_e64 s[10:11], s10, v156
	s_and_b64 s[12:13], s[14:15], s[12:13]
	v_cmp_lt_i32_e64 s[8:9], s8, v156
	s_and_b64 s[10:11], s[12:13], s[10:11]
	s_and_b64 s[8:9], s[10:11], s[8:9]
	s_and_b64 vcc, s[8:9], vcc
	v_cndmask_b32_e64 v81, v81, v127, s[64:65]
	v_cndmask_b32_e64 v80, v80, v127, s[62:63]
	v_cndmask_b32_e64 v79, v79, v127, s[60:61]
	v_cndmask_b32_e64 v78, v78, v127, s[58:59]
	v_cndmask_b32_e64 v77, v77, v127, s[56:57]
	v_cndmask_b32_e64 v76, v76, v127, s[54:55]
	v_cndmask_b32_e64 v75, v75, v127, s[52:53]
	v_cndmask_b32_e64 v74, v74, v127, s[50:51]
	v_cndmask_b32_e64 v73, v73, v127, s[48:49]
	v_cndmask_b32_e64 v72, v72, v127, s[46:47]
	v_cndmask_b32_e64 v71, v71, v127, s[44:45]
	v_cndmask_b32_e64 v70, v70, v127, s[42:43]
	v_cndmask_b32_e64 v69, v69, v127, s[40:41]
	v_cndmask_b32_e64 v97, v97, v127, s[38:39]
	v_cndmask_b32_e64 v96, v96, v127, s[36:37]
	v_cndmask_b32_e64 v95, v95, v127, s[34:35]
	v_cndmask_b32_e64 v94, v94, v127, s[30:31]
	v_cndmask_b32_e64 v93, v93, v127, s[28:29]
	v_cndmask_b32_e64 v92, v92, v127, s[26:27]
	v_cndmask_b32_e64 v91, v91, v127, s[24:25]
	v_cndmask_b32_e64 v90, v90, v127, s[22:23]
	v_cndmask_b32_e64 v89, v89, v127, s[20:21]
	v_cndmask_b32_e64 v88, v88, v127, s[18:19]
	v_cndmask_b32_e64 v87, v87, v127, s[16:17]
	v_cndmask_b32_e64 v86, v86, v127, s[14:15]
	v_cndmask_b32_e64 v85, v85, v127, s[12:13]
	v_cndmask_b32_e64 v84, v84, v127, s[10:11]
	v_cndmask_b32_e64 v83, v83, v127, s[8:9]
	v_cndmask_b32_e32 v82, v82, v127, vcc

.LBB0_839:
	ds_read_b128 v[26:29], v183
	ds_read_b128 v[30:33], v183 offset:16
	ds_read_b128 v[18:21], v183 offset:2048
	ds_read_b128 v[22:25], v183 offset:2064
	ds_read_b128 v[10:13], v184
	ds_read_b128 v[14:17], v184 offset:16
	ds_read_b128 v[2:5], v184 offset:2048
	ds_read_b128 v[6:9], v184 offset:2064
	s_add_u32 s30, s28, 0xfffc0080
	s_addc_u32 s31, s29, -1
	s_cmp_eq_u32 s53, 12
	s_cselect_b32 s35, s21, s31
	s_cselect_b32 s34, s49, s30
	s_cselect_b32 s31, s19, s52
	s_cselect_b32 s30, s50, s51
	s_add_i32 m0, s27, 0xc000
	ds_read_b128 v[174:177], v185
	ds_read_b128 v[178:181], v185 offset:16
	ds_read_b128 v[188:191], v185 offset:2048
	ds_read_b128 v[192:195], v185 offset:2064
	ds_read_b128 v[196:199], v185 offset:4096
	ds_read_b128 v[200:203], v185 offset:4112
	ds_read_b128 v[204:207], v185 offset:6144
	ds_read_b128 v[208:211], v185 offset:6160
	global_load_lds_dwordx4 v162, s[28:29]
	s_add_i32 m0, s27, 0xe000
	s_nop 0
	global_load_lds_dwordx4 v172, s[28:29]
	s_waitcnt vmcnt(8)
	s_waitcnt lgkmcnt(0)
	s_barrier
	s_setprio 1
	v_mfma_f32_16x16x128_f8f6f4 v[158:161], v[26:33], v[174:181], v[158:161]
	v_mfma_f32_16x16x128_f8f6f4 v[154:157], v[18:25], v[174:181], v[154:157]
	v_mfma_f32_16x16x128_f8f6f4 v[142:145], v[26:33], v[188:195], v[142:145]
	v_mfma_f32_16x16x128_f8f6f4 v[138:141], v[18:25], v[188:195], v[138:141]
	v_mfma_f32_16x16x128_f8f6f4 v[126:129], v[26:33], v[196:203], v[126:129]
	v_mfma_f32_16x16x128_f8f6f4 v[122:125], v[18:25], v[196:203], v[122:125]
	v_mfma_f32_16x16x128_f8f6f4 v[110:113], v[26:33], v[204:211], v[110:113]
	v_mfma_f32_16x16x128_f8f6f4 v[106:109], v[18:25], v[204:211], v[106:109]
	v_mfma_f32_16x16x128_f8f6f4 v[150:153], v[10:17], v[174:181], v[150:153]
	v_mfma_f32_16x16x128_f8f6f4 v[146:149], v[2:9], v[174:181], v[146:149]
	v_mfma_f32_16x16x128_f8f6f4 v[134:137], v[10:17], v[188:195], v[134:137]
	v_mfma_f32_16x16x128_f8f6f4 v[130:133], v[2:9], v[188:195], v[130:133]
	v_mfma_f32_16x16x128_f8f6f4 v[118:121], v[10:17], v[196:203], v[118:121]
	v_mfma_f32_16x16x128_f8f6f4 v[114:117], v[2:9], v[196:203], v[114:117]
	v_mfma_f32_16x16x128_f8f6f4 v[102:105], v[10:17], v[204:211], v[102:105]
	v_mfma_f32_16x16x128_f8f6f4 v[98:101], v[2:9], v[204:211], v[98:101]
	s_setprio 0
	s_barrier
	s_add_i32 s54, s46, s36
	s_mov_b32 m0, s54
	ds_read_b128 v[188:191], v185 offset:16384
	ds_read_b128 v[192:195], v185 offset:16400
	ds_read_b128 v[196:199], v185 offset:18432
	ds_read_b128 v[200:203], v185 offset:18448
	ds_read_b128 v[204:207], v185 offset:20480
	ds_read_b128 v[208:211], v185 offset:20496
	ds_read_b128 v[212:215], v185 offset:22528
	ds_read_b128 v[216:219], v185 offset:22544
	global_load_lds_dwordx4 v168, s[30:31]
	s_add_i32 m0, s54, 0x2000
	s_add_u32 s54, s30, 0x40000
	s_addc_u32 s55, s31, 0
	s_add_i32 s56, s47, s36
	global_load_lds_dwordx4 v170, s[30:31]
	s_mov_b32 m0, s56
	global_load_lds_dwordx4 v168, s[54:55]
	s_add_i32 m0, s56, 0x2000
	s_nop 0
	global_load_lds_dwordx4 v170, s[54:55]
	s_mov_b32 m0, s27
	s_nop 0
	global_load_lds_dwordx4 v162, s[34:35]
	s_mov_b32 m0, s37
	s_nop 0
	global_load_lds_dwordx4 v172, s[34:35]
	s_waitcnt vmcnt(8)
	s_waitcnt lgkmcnt(0)
	s_barrier
	s_setprio 1
	v_mfma_f32_16x16x128_f8f6f4 v[94:97], v[26:33], v[188:195], v[94:97]
	v_mfma_f32_16x16x128_f8f6f4 v[90:93], v[18:25], v[188:195], v[90:93]
	v_mfma_f32_16x16x128_f8f6f4 v[78:81], v[26:33], v[196:203], v[78:81]
	v_mfma_f32_16x16x128_f8f6f4 v[74:77], v[18:25], v[196:203], v[74:77]
	v_mfma_f32_16x16x128_f8f6f4 v[62:65], v[26:33], v[204:211], v[62:65]
	v_mfma_f32_16x16x128_f8f6f4 v[58:61], v[18:25], v[204:211], v[58:61]
	v_mfma_f32_16x16x128_f8f6f4 v[46:49], v[26:33], v[212:219], v[46:49]
	v_mfma_f32_16x16x128_f8f6f4 v[42:45], v[18:25], v[212:219], v[42:45]
	v_mfma_f32_16x16x128_f8f6f4 v[86:89], v[10:17], v[188:195], v[86:89]
	v_mfma_f32_16x16x128_f8f6f4 v[82:85], v[2:9], v[188:195], v[82:85]
	v_mfma_f32_16x16x128_f8f6f4 v[70:73], v[10:17], v[196:203], v[70:73]
	v_mfma_f32_16x16x128_f8f6f4 v[66:69], v[2:9], v[196:203], v[66:69]
	v_mfma_f32_16x16x128_f8f6f4 v[54:57], v[10:17], v[204:211], v[54:57]
	v_mfma_f32_16x16x128_f8f6f4 v[50:53], v[2:9], v[204:211], v[50:53]
	v_mfma_f32_16x16x128_f8f6f4 v[38:41], v[10:17], v[212:219], v[38:41]
	v_mfma_f32_16x16x128_f8f6f4 v[34:37], v[2:9], v[212:219], v[34:37]
	s_setprio 0
	s_barrier
	s_add_i32 s54, 0, 0x18000
	s_add_i32 s55, 0, 0x1c000
	v_add_u32_e32 v14, s54, v182
	v_add_u32_e32 v30, s55, v182
	ds_read_b128 v[2:5], v14
	ds_read_b128 v[6:9], v14 offset:16
	ds_read_b128 v[10:13], v14 offset:2048
	ds_read_b128 v[14:17], v14 offset:2064
	ds_read_b128 v[18:21], v30
	ds_read_b128 v[22:25], v30 offset:16
	ds_read_b128 v[26:29], v30 offset:2048
	ds_read_b128 v[30:33], v30 offset:2064
	s_add_u32 s98, s34, 0x80
	s_addc_u32 s99, s35, 0
	s_add_u32 s34, s34, 0x40000
	s_addc_u32 s35, s35, 0
	s_mov_b32 m0, s38
	ds_read_b128 v[188:191], v185 offset:32768
	ds_read_b128 v[192:195], v185 offset:32784
	ds_read_b128 v[196:199], v185 offset:34816
	ds_read_b128 v[200:203], v185 offset:34832
	ds_read_b128 v[204:207], v185 offset:36864
	ds_read_b128 v[208:211], v185 offset:36880
	ds_read_b128 v[212:215], v185 offset:38912
	ds_read_b128 v[216:219], v185 offset:38928
	global_load_lds_dwordx4 v162, s[34:35]
	s_mov_b32 m0, s39
	s_nop 0
	global_load_lds_dwordx4 v172, s[34:35]
	s_waitcnt vmcnt(8)
	s_waitcnt lgkmcnt(0)
	s_barrier
	s_setprio 1
	v_mfma_f32_16x16x128_f8f6f4 v[158:161], v[2:9], v[188:195], v[158:161]
	v_mfma_f32_16x16x128_f8f6f4 v[154:157], v[10:17], v[188:195], v[154:157]
	v_mfma_f32_16x16x128_f8f6f4 v[142:145], v[2:9], v[196:203], v[142:145]
	v_mfma_f32_16x16x128_f8f6f4 v[138:141], v[10:17], v[196:203], v[138:141]
	v_mfma_f32_16x16x128_f8f6f4 v[126:129], v[2:9], v[204:211], v[126:129]
	v_mfma_f32_16x16x128_f8f6f4 v[122:125], v[10:17], v[204:211], v[122:125]
	v_mfma_f32_16x16x128_f8f6f4 v[110:113], v[2:9], v[212:219], v[110:113]
	v_mfma_f32_16x16x128_f8f6f4 v[106:109], v[10:17], v[212:219], v[106:109]
	v_mfma_f32_16x16x128_f8f6f4 v[150:153], v[18:25], v[188:195], v[150:153]
	v_mfma_f32_16x16x128_f8f6f4 v[146:149], v[26:33], v[188:195], v[146:149]
	v_mfma_f32_16x16x128_f8f6f4 v[134:137], v[18:25], v[196:203], v[134:137]
	v_mfma_f32_16x16x128_f8f6f4 v[130:133], v[26:33], v[196:203], v[130:133]
	v_mfma_f32_16x16x128_f8f6f4 v[118:121], v[18:25], v[204:211], v[118:121]
	v_mfma_f32_16x16x128_f8f6f4 v[114:117], v[26:33], v[204:211], v[114:117]
	v_mfma_f32_16x16x128_f8f6f4 v[102:105], v[18:25], v[212:219], v[102:105]
	v_mfma_f32_16x16x128_f8f6f4 v[98:101], v[26:33], v[212:219], v[98:101]
	s_setprio 0
	s_barrier
	s_add_i32 s34, s54, s36
	s_mov_b32 m0, s34
	ds_read_b128 v[188:191], v185 offset:49152
	ds_read_b128 v[192:195], v185 offset:49168
	ds_read_b128 v[196:199], v185 offset:51200
	ds_read_b128 v[200:203], v185 offset:51216
	ds_read_b128 v[204:207], v185 offset:53248
	ds_read_b128 v[208:211], v185 offset:53264
	ds_read_b128 v[212:215], v185 offset:55296
	ds_read_b128 v[216:219], v185 offset:55312
	s_add_u32 s30, s30, 0x80
	s_addc_u32 s31, s31, 0
	global_load_lds_dwordx4 v168, s[30:31]
	s_add_i32 m0, s34, 0x2000
	s_add_i32 s34, s55, s36
	global_load_lds_dwordx4 v170, s[30:31]
	s_add_u32 s30, s30, 0x40000
	s_addc_u32 s31, s31, 0
	s_mov_b32 m0, s34
	s_nop 0
	global_load_lds_dwordx4 v168, s[30:31]
	s_add_i32 m0, s34, 0x2000
	s_nop 0
	global_load_lds_dwordx4 v170, s[30:31]
	s_mov_b32 m0, s43
	s_nop 0
	global_load_lds_dwordx4 v162, s[98:99]
	s_mov_b32 m0, s44
	s_nop 0
	global_load_lds_dwordx4 v172, s[98:99]
	s_waitcnt vmcnt(8)
	s_waitcnt lgkmcnt(0)
	s_barrier
	s_setprio 1
	v_mfma_f32_16x16x128_f8f6f4 v[94:97], v[2:9], v[188:195], v[94:97]
	v_mfma_f32_16x16x128_f8f6f4 v[90:93], v[10:17], v[188:195], v[90:93]
	v_mfma_f32_16x16x128_f8f6f4 v[78:81], v[2:9], v[196:203], v[78:81]
	v_mfma_f32_16x16x128_f8f6f4 v[74:77], v[10:17], v[196:203], v[74:77]
	v_mfma_f32_16x16x128_f8f6f4 v[62:65], v[2:9], v[204:211], v[62:65]
	v_mfma_f32_16x16x128_f8f6f4 v[58:61], v[10:17], v[204:211], v[58:61]
	v_mfma_f32_16x16x128_f8f6f4 v[46:49], v[2:9], v[212:219], v[46:49]
	v_mfma_f32_16x16x128_f8f6f4 v[42:45], v[10:17], v[212:219], v[42:45]
	v_mfma_f32_16x16x128_f8f6f4 v[86:89], v[18:25], v[188:195], v[86:89]
	v_mfma_f32_16x16x128_f8f6f4 v[82:85], v[26:33], v[188:195], v[82:85]
	v_mfma_f32_16x16x128_f8f6f4 v[70:73], v[18:25], v[196:203], v[70:73]
	v_mfma_f32_16x16x128_f8f6f4 v[66:69], v[26:33], v[196:203], v[66:69]
	v_mfma_f32_16x16x128_f8f6f4 v[54:57], v[18:25], v[204:211], v[54:57]
	v_mfma_f32_16x16x128_f8f6f4 v[50:53], v[26:33], v[204:211], v[50:53]
	v_mfma_f32_16x16x128_f8f6f4 v[38:41], v[18:25], v[212:219], v[38:41]
	v_mfma_f32_16x16x128_f8f6f4 v[34:37], v[26:33], v[212:219], v[34:37]
	s_setprio 0
	s_barrier
	s_add_i32 s53, s53, 2
	s_add_u32 s28, s28, 0x100
	s_addc_u32 s29, s29, 0
	s_add_u32 s51, s51, 0x100
	s_addc_u32 s52, s52, 0
	s_cmp_gt_u32 s53, 13
	s_cbranch_scc0 .LBB0_839
	s_and_b64 vcc, exec, s[10:11]
	s_cbranch_vccz .LBB0_842
	s_barrier

.LBB0_863:
	ds_read_b128 v[146:149], v154
	ds_read_b128 v[158:161], v154 offset:1024
	ds_read_b128 v[162:165], v154 offset:2048
	ds_read_b128 v[166:169], v154 offset:3072
	ds_read_b128 v[170:173], v155
	ds_read_b128 v[174:177], v155 offset:1024
	ds_read_b128 v[178:181], v155 offset:2048
	ds_read_b128 v[182:185], v155 offset:3072
	s_add_u32 s22, s20, 0xfff80080
	s_addc_u32 s23, s21, -1
	s_cmp_eq_u32 s43, 28
	s_cselect_b32 s25, s13, s23
	s_cselect_b32 s24, s39, s22
	s_cselect_b32 s23, s11, s42
	s_cselect_b32 s22, s40, s41
	s_add_i32 m0, s19, 0xc000
	ds_read_b128 v[186:189], v156
	ds_read_b128 v[190:193], v156 offset:1024
	ds_read_b128 v[194:197], v156 offset:2048
	ds_read_b128 v[198:201], v156 offset:3072
	ds_read_b128 v[202:205], v156 offset:4096
	ds_read_b128 v[206:209], v156 offset:5120
	ds_read_b128 v[210:213], v156 offset:6144
	ds_read_b128 v[214:217], v156 offset:7168
	global_load_lds_dwordx4 v138, s[20:21]
	s_add_i32 m0, s19, 0xe000
	s_nop 0
	global_load_lds_dwordx4 v140, s[20:21]
	s_waitcnt vmcnt(8)
	s_waitcnt lgkmcnt(0)
	s_barrier
	s_setprio 1
	v_mfma_f32_16x16x32_bf16 v[126:129], v[146:149], v[186:189], v[126:129]
	v_mfma_f32_16x16x32_bf16 v[126:129], v[158:161], v[190:193], v[126:129]
	v_mfma_f32_16x16x32_bf16 v[122:125], v[162:165], v[186:189], v[122:125]
	v_mfma_f32_16x16x32_bf16 v[122:125], v[166:169], v[190:193], v[122:125]
	v_mfma_f32_16x16x32_bf16 v[110:113], v[146:149], v[194:197], v[110:113]
	v_mfma_f32_16x16x32_bf16 v[110:113], v[158:161], v[198:201], v[110:113]
	v_mfma_f32_16x16x32_bf16 v[106:109], v[162:165], v[194:197], v[106:109]
	v_mfma_f32_16x16x32_bf16 v[106:109], v[166:169], v[198:201], v[106:109]
	v_mfma_f32_16x16x32_bf16 v[94:97], v[146:149], v[202:205], v[94:97]
	v_mfma_f32_16x16x32_bf16 v[94:97], v[158:161], v[206:209], v[94:97]
	v_mfma_f32_16x16x32_bf16 v[90:93], v[162:165], v[202:205], v[90:93]
	v_mfma_f32_16x16x32_bf16 v[90:93], v[166:169], v[206:209], v[90:93]
	v_mfma_f32_16x16x32_bf16 v[78:81], v[146:149], v[210:213], v[78:81]
	v_mfma_f32_16x16x32_bf16 v[78:81], v[158:161], v[214:217], v[78:81]
	v_mfma_f32_16x16x32_bf16 v[74:77], v[162:165], v[210:213], v[74:77]
	v_mfma_f32_16x16x32_bf16 v[74:77], v[166:169], v[214:217], v[74:77]
	v_mfma_f32_16x16x32_bf16 v[118:121], v[170:173], v[186:189], v[118:121]
	v_mfma_f32_16x16x32_bf16 v[118:121], v[174:177], v[190:193], v[118:121]
	v_mfma_f32_16x16x32_bf16 v[114:117], v[178:181], v[186:189], v[114:117]
	v_mfma_f32_16x16x32_bf16 v[114:117], v[182:185], v[190:193], v[114:117]
	v_mfma_f32_16x16x32_bf16 v[102:105], v[170:173], v[194:197], v[102:105]
	v_mfma_f32_16x16x32_bf16 v[102:105], v[174:177], v[198:201], v[102:105]
	v_mfma_f32_16x16x32_bf16 v[98:101], v[178:181], v[194:197], v[98:101]
	v_mfma_f32_16x16x32_bf16 v[98:101], v[182:185], v[198:201], v[98:101]
	v_mfma_f32_16x16x32_bf16 v[86:89], v[170:173], v[202:205], v[86:89]
	v_mfma_f32_16x16x32_bf16 v[86:89], v[174:177], v[206:209], v[86:89]
	v_mfma_f32_16x16x32_bf16 v[82:85], v[178:181], v[202:205], v[82:85]
	v_mfma_f32_16x16x32_bf16 v[82:85], v[182:185], v[206:209], v[82:85]
	v_mfma_f32_16x16x32_bf16 v[70:73], v[170:173], v[210:213], v[70:73]
	v_mfma_f32_16x16x32_bf16 v[70:73], v[174:177], v[214:217], v[70:73]
	v_mfma_f32_16x16x32_bf16 v[66:69], v[178:181], v[210:213], v[66:69]
	v_mfma_f32_16x16x32_bf16 v[66:69], v[182:185], v[214:217], v[66:69]
	s_setprio 0
	s_barrier
	s_add_i32 s44, s36, s27
	s_mov_b32 m0, s44
	ds_read_b128 v[186:189], v156 offset:16384
	ds_read_b128 v[190:193], v156 offset:17408
	ds_read_b128 v[194:197], v156 offset:18432
	ds_read_b128 v[198:201], v156 offset:19456
	ds_read_b128 v[202:205], v156 offset:20480
	ds_read_b128 v[206:209], v156 offset:21504
	ds_read_b128 v[210:213], v156 offset:22528
	ds_read_b128 v[214:217], v156 offset:23552
	global_load_lds_dwordx4 v132, s[22:23]
	s_add_i32 m0, s44, 0x2000
	s_add_u32 s44, s22, 0x80000
	s_addc_u32 s45, s23, 0
	s_add_i32 s46, s37, s27
	global_load_lds_dwordx4 v136, s[22:23]
	s_mov_b32 m0, s46
	global_load_lds_dwordx4 v132, s[44:45]
	s_add_i32 m0, s46, 0x2000
	s_nop 0
	global_load_lds_dwordx4 v136, s[44:45]
	s_mov_b32 m0, s19
	s_nop 0
	global_load_lds_dwordx4 v130, s[24:25]
	s_mov_b32 m0, s28
	s_nop 0
	global_load_lds_dwordx4 v134, s[24:25]
	s_waitcnt vmcnt(8)
	s_waitcnt lgkmcnt(0)
	s_barrier
	s_setprio 1
	v_mfma_f32_16x16x32_bf16 v[62:65], v[146:149], v[186:189], v[62:65]
	v_mfma_f32_16x16x32_bf16 v[62:65], v[158:161], v[190:193], v[62:65]
	v_mfma_f32_16x16x32_bf16 v[58:61], v[162:165], v[186:189], v[58:61]
	v_mfma_f32_16x16x32_bf16 v[58:61], v[166:169], v[190:193], v[58:61]
	v_mfma_f32_16x16x32_bf16 v[46:49], v[146:149], v[194:197], v[46:49]
	v_mfma_f32_16x16x32_bf16 v[46:49], v[158:161], v[198:201], v[46:49]
	v_mfma_f32_16x16x32_bf16 v[42:45], v[162:165], v[194:197], v[42:45]
	v_mfma_f32_16x16x32_bf16 v[42:45], v[166:169], v[198:201], v[42:45]
	v_mfma_f32_16x16x32_bf16 v[30:33], v[146:149], v[202:205], v[30:33]
	v_mfma_f32_16x16x32_bf16 v[30:33], v[158:161], v[206:209], v[30:33]
	v_mfma_f32_16x16x32_bf16 v[26:29], v[162:165], v[202:205], v[26:29]
	v_mfma_f32_16x16x32_bf16 v[26:29], v[166:169], v[206:209], v[26:29]
	v_mfma_f32_16x16x32_bf16 v[14:17], v[146:149], v[210:213], v[14:17]
	v_mfma_f32_16x16x32_bf16 v[14:17], v[158:161], v[214:217], v[14:17]
	v_mfma_f32_16x16x32_bf16 v[10:13], v[162:165], v[210:213], v[10:13]
	v_mfma_f32_16x16x32_bf16 v[10:13], v[166:169], v[214:217], v[10:13]
	v_mfma_f32_16x16x32_bf16 v[54:57], v[170:173], v[186:189], v[54:57]
	v_mfma_f32_16x16x32_bf16 v[54:57], v[174:177], v[190:193], v[54:57]
	v_mfma_f32_16x16x32_bf16 v[50:53], v[178:181], v[186:189], v[50:53]
	v_mfma_f32_16x16x32_bf16 v[50:53], v[182:185], v[190:193], v[50:53]
	v_mfma_f32_16x16x32_bf16 v[38:41], v[170:173], v[194:197], v[38:41]
	v_mfma_f32_16x16x32_bf16 v[38:41], v[174:177], v[198:201], v[38:41]
	v_mfma_f32_16x16x32_bf16 v[34:37], v[178:181], v[194:197], v[34:37]
	v_mfma_f32_16x16x32_bf16 v[34:37], v[182:185], v[198:201], v[34:37]
	v_mfma_f32_16x16x32_bf16 v[22:25], v[170:173], v[202:205], v[22:25]
	v_mfma_f32_16x16x32_bf16 v[22:25], v[174:177], v[206:209], v[22:25]
	v_mfma_f32_16x16x32_bf16 v[18:21], v[178:181], v[202:205], v[18:21]
	v_mfma_f32_16x16x32_bf16 v[18:21], v[182:185], v[206:209], v[18:21]
	v_mfma_f32_16x16x32_bf16 v[6:9], v[170:173], v[210:213], v[6:9]
	v_mfma_f32_16x16x32_bf16 v[6:9], v[174:177], v[214:217], v[6:9]
	v_mfma_f32_16x16x32_bf16 v[2:5], v[178:181], v[210:213], v[2:5]
	v_mfma_f32_16x16x32_bf16 v[2:5], v[182:185], v[214:217], v[2:5]
	s_setprio 0
	s_barrier
	s_add_i32 s44, 0, 0x18000
	v_add_u32_e32 v157, s44, v152
	s_add_i32 s45, 0, 0x1c000
	ds_read_b128 v[146:149], v157
	ds_read_b128 v[158:161], v157 offset:1024
	ds_read_b128 v[162:165], v157 offset:2048
	ds_read_b128 v[166:169], v157 offset:3072
	v_add_u32_e32 v157, s45, v152
	ds_read_b128 v[170:173], v157
	ds_read_b128 v[174:177], v157 offset:1024
	ds_read_b128 v[178:181], v157 offset:2048
	ds_read_b128 v[182:185], v157 offset:3072
	s_add_u32 s98, s24, 0x80
	s_addc_u32 s99, s25, 0
	s_add_u32 s24, s24, 0x80000
	s_addc_u32 s25, s25, 0
	s_mov_b32 m0, s29
	ds_read_b128 v[186:189], v156 offset:32768
	ds_read_b128 v[190:193], v156 offset:33792
	ds_read_b128 v[194:197], v156 offset:34816
	ds_read_b128 v[198:201], v156 offset:35840
	ds_read_b128 v[202:205], v156 offset:36864
	ds_read_b128 v[206:209], v156 offset:37888
	ds_read_b128 v[210:213], v156 offset:38912
	ds_read_b128 v[214:217], v156 offset:39936
	global_load_lds_dwordx4 v130, s[24:25]
	s_mov_b32 m0, s30
	s_nop 0
	global_load_lds_dwordx4 v134, s[24:25]
	s_waitcnt vmcnt(8)
	s_waitcnt lgkmcnt(0)
	s_barrier
	s_setprio 1
	v_mfma_f32_16x16x32_bf16 v[126:129], v[146:149], v[186:189], v[126:129]
	v_mfma_f32_16x16x32_bf16 v[126:129], v[158:161], v[190:193], v[126:129]
	v_mfma_f32_16x16x32_bf16 v[122:125], v[162:165], v[186:189], v[122:125]
	v_mfma_f32_16x16x32_bf16 v[122:125], v[166:169], v[190:193], v[122:125]
	v_mfma_f32_16x16x32_bf16 v[110:113], v[146:149], v[194:197], v[110:113]
	v_mfma_f32_16x16x32_bf16 v[110:113], v[158:161], v[198:201], v[110:113]
	v_mfma_f32_16x16x32_bf16 v[106:109], v[162:165], v[194:197], v[106:109]
	v_mfma_f32_16x16x32_bf16 v[106:109], v[166:169], v[198:201], v[106:109]
	v_mfma_f32_16x16x32_bf16 v[94:97], v[146:149], v[202:205], v[94:97]
	v_mfma_f32_16x16x32_bf16 v[94:97], v[158:161], v[206:209], v[94:97]
	v_mfma_f32_16x16x32_bf16 v[90:93], v[162:165], v[202:205], v[90:93]
	v_mfma_f32_16x16x32_bf16 v[90:93], v[166:169], v[206:209], v[90:93]
	v_mfma_f32_16x16x32_bf16 v[78:81], v[146:149], v[210:213], v[78:81]
	v_mfma_f32_16x16x32_bf16 v[78:81], v[158:161], v[214:217], v[78:81]
	v_mfma_f32_16x16x32_bf16 v[74:77], v[162:165], v[210:213], v[74:77]
	v_mfma_f32_16x16x32_bf16 v[74:77], v[166:169], v[214:217], v[74:77]
	v_mfma_f32_16x16x32_bf16 v[118:121], v[170:173], v[186:189], v[118:121]
	v_mfma_f32_16x16x32_bf16 v[118:121], v[174:177], v[190:193], v[118:121]
	v_mfma_f32_16x16x32_bf16 v[114:117], v[178:181], v[186:189], v[114:117]
	v_mfma_f32_16x16x32_bf16 v[114:117], v[182:185], v[190:193], v[114:117]
	v_mfma_f32_16x16x32_bf16 v[102:105], v[170:173], v[194:197], v[102:105]
	v_mfma_f32_16x16x32_bf16 v[102:105], v[174:177], v[198:201], v[102:105]
	v_mfma_f32_16x16x32_bf16 v[98:101], v[178:181], v[194:197], v[98:101]
	v_mfma_f32_16x16x32_bf16 v[98:101], v[182:185], v[198:201], v[98:101]
	v_mfma_f32_16x16x32_bf16 v[86:89], v[170:173], v[202:205], v[86:89]
	v_mfma_f32_16x16x32_bf16 v[86:89], v[174:177], v[206:209], v[86:89]
	v_mfma_f32_16x16x32_bf16 v[82:85], v[178:181], v[202:205], v[82:85]
	v_mfma_f32_16x16x32_bf16 v[82:85], v[182:185], v[206:209], v[82:85]
	v_mfma_f32_16x16x32_bf16 v[70:73], v[170:173], v[210:213], v[70:73]
	v_mfma_f32_16x16x32_bf16 v[70:73], v[174:177], v[214:217], v[70:73]
	v_mfma_f32_16x16x32_bf16 v[66:69], v[178:181], v[210:213], v[66:69]
	v_mfma_f32_16x16x32_bf16 v[66:69], v[182:185], v[214:217], v[66:69]
	s_setprio 0
	s_barrier
	s_add_i32 s24, s44, s27
	s_mov_b32 m0, s24
	ds_read_b128 v[186:189], v156 offset:49152
	ds_read_b128 v[190:193], v156 offset:50176
	ds_read_b128 v[194:197], v156 offset:51200
	ds_read_b128 v[198:201], v156 offset:52224
	ds_read_b128 v[202:205], v156 offset:53248
	ds_read_b128 v[206:209], v156 offset:54272
	ds_read_b128 v[210:213], v156 offset:55296
	ds_read_b128 v[214:217], v156 offset:56320
	s_add_u32 s22, s22, 0x80
	s_addc_u32 s23, s23, 0
	global_load_lds_dwordx4 v132, s[22:23]
	s_add_i32 m0, s24, 0x2000
	s_add_i32 s24, s45, s27
	global_load_lds_dwordx4 v136, s[22:23]
	s_add_u32 s22, s22, 0x80000
	s_addc_u32 s23, s23, 0
	s_mov_b32 m0, s24
	s_nop 0
	global_load_lds_dwordx4 v132, s[22:23]
	s_add_i32 m0, s24, 0x2000
	s_nop 0
	global_load_lds_dwordx4 v136, s[22:23]
	s_mov_b32 m0, s33
	s_nop 0
	global_load_lds_dwordx4 v130, s[98:99]
	s_mov_b32 m0, s34
	s_nop 0
	global_load_lds_dwordx4 v134, s[98:99]
	s_waitcnt vmcnt(8)
	s_waitcnt lgkmcnt(0)
	s_barrier
	s_setprio 1
	v_mfma_f32_16x16x32_bf16 v[62:65], v[146:149], v[186:189], v[62:65]
	v_mfma_f32_16x16x32_bf16 v[62:65], v[158:161], v[190:193], v[62:65]
	v_mfma_f32_16x16x32_bf16 v[58:61], v[162:165], v[186:189], v[58:61]
	v_mfma_f32_16x16x32_bf16 v[58:61], v[166:169], v[190:193], v[58:61]
	v_mfma_f32_16x16x32_bf16 v[46:49], v[146:149], v[194:197], v[46:49]
	v_mfma_f32_16x16x32_bf16 v[46:49], v[158:161], v[198:201], v[46:49]
	v_mfma_f32_16x16x32_bf16 v[42:45], v[162:165], v[194:197], v[42:45]
	v_mfma_f32_16x16x32_bf16 v[42:45], v[166:169], v[198:201], v[42:45]
	v_mfma_f32_16x16x32_bf16 v[30:33], v[146:149], v[202:205], v[30:33]
	v_mfma_f32_16x16x32_bf16 v[30:33], v[158:161], v[206:209], v[30:33]
	v_mfma_f32_16x16x32_bf16 v[26:29], v[162:165], v[202:205], v[26:29]
	v_mfma_f32_16x16x32_bf16 v[26:29], v[166:169], v[206:209], v[26:29]
	v_mfma_f32_16x16x32_bf16 v[14:17], v[146:149], v[210:213], v[14:17]
	v_mfma_f32_16x16x32_bf16 v[14:17], v[158:161], v[214:217], v[14:17]
	v_mfma_f32_16x16x32_bf16 v[10:13], v[162:165], v[210:213], v[10:13]
	v_mfma_f32_16x16x32_bf16 v[10:13], v[166:169], v[214:217], v[10:13]
	v_mfma_f32_16x16x32_bf16 v[54:57], v[170:173], v[186:189], v[54:57]
	v_mfma_f32_16x16x32_bf16 v[54:57], v[174:177], v[190:193], v[54:57]
	v_mfma_f32_16x16x32_bf16 v[50:53], v[178:181], v[186:189], v[50:53]
	v_mfma_f32_16x16x32_bf16 v[50:53], v[182:185], v[190:193], v[50:53]
	v_mfma_f32_16x16x32_bf16 v[38:41], v[170:173], v[194:197], v[38:41]
	v_mfma_f32_16x16x32_bf16 v[38:41], v[174:177], v[198:201], v[38:41]
	v_mfma_f32_16x16x32_bf16 v[34:37], v[178:181], v[194:197], v[34:37]
	v_mfma_f32_16x16x32_bf16 v[34:37], v[182:185], v[198:201], v[34:37]
	v_mfma_f32_16x16x32_bf16 v[22:25], v[170:173], v[202:205], v[22:25]
	v_mfma_f32_16x16x32_bf16 v[22:25], v[174:177], v[206:209], v[22:25]
	v_mfma_f32_16x16x32_bf16 v[18:21], v[178:181], v[202:205], v[18:21]
	v_mfma_f32_16x16x32_bf16 v[18:21], v[182:185], v[206:209], v[18:21]
	v_mfma_f32_16x16x32_bf16 v[6:9], v[170:173], v[210:213], v[6:9]
	v_mfma_f32_16x16x32_bf16 v[6:9], v[174:177], v[214:217], v[6:9]
	v_mfma_f32_16x16x32_bf16 v[2:5], v[178:181], v[210:213], v[2:5]
	v_mfma_f32_16x16x32_bf16 v[2:5], v[182:185], v[214:217], v[2:5]
	s_setprio 0
	s_barrier
	s_add_i32 s43, s43, 2
	s_add_u32 s20, s20, 0x100
	s_addc_u32 s21, s21, 0
	s_add_u32 s41, s41, 0x100
	s_addc_u32 s42, s42, 0
	s_cmp_gt_u32 s43, 29
	s_cbranch_scc0 .LBB0_863
	s_and_b64 vcc, exec, s[8:9]
	s_cbranch_vccz .LBB0_866
	s_barrier

.LBB0_941:
	ds_read_b128 v[90:93], v188
	ds_read_b128 v[94:97], v188 offset:1024
	ds_read_b128 v[102:105], v188 offset:2048
	ds_read_b128 v[110:113], v188 offset:3072
	ds_read_b128 v[146:149], v189
	ds_read_b128 v[150:153], v189 offset:1024
	ds_read_b128 v[154:157], v189 offset:2048
	ds_read_b128 v[158:161], v189 offset:3072
	s_add_u32 s30, s28, 0xfff00080
	s_addc_u32 s31, s29, -1
	s_cmp_eq_u32 s51, 60
	s_cselect_b32 s35, s21, s31
	s_cselect_b32 s34, s27, s30
	s_cselect_b32 s31, s19, s50
	s_cselect_b32 s30, s48, s49
	s_add_i32 m0, s36, 0xc000
	ds_read_b128 v[178:181], v190
	ds_read_b128 v[182:185], v190 offset:1024
	ds_read_b128 v[192:195], v190 offset:2048
	ds_read_b128 v[196:199], v190 offset:3072
	ds_read_b128 v[200:203], v190 offset:4096
	ds_read_b128 v[204:207], v190 offset:5120
	ds_read_b128 v[208:211], v190 offset:6144
	ds_read_b128 v[212:215], v190 offset:7168
	global_load_lds_dwordx4 v170, s[28:29]
	s_add_i32 m0, s36, 0xe000
	s_nop 0
	global_load_lds_dwordx4 v172, s[28:29]
	s_waitcnt vmcnt(8)
	s_waitcnt lgkmcnt(0)
	s_barrier
	s_setprio 1
	v_mfma_f32_16x16x32_bf16 v[142:145], v[90:93], v[178:181], v[142:145]
	v_mfma_f32_16x16x32_bf16 v[142:145], v[94:97], v[182:185], v[142:145]
	v_mfma_f32_16x16x32_bf16 v[138:141], v[102:105], v[178:181], v[138:141]
	v_mfma_f32_16x16x32_bf16 v[138:141], v[110:113], v[182:185], v[138:141]
	v_mfma_f32_16x16x32_bf16 v[126:129], v[90:93], v[192:195], v[126:129]
	v_mfma_f32_16x16x32_bf16 v[126:129], v[94:97], v[196:199], v[126:129]
	v_mfma_f32_16x16x32_bf16 v[122:125], v[102:105], v[192:195], v[122:125]
	v_mfma_f32_16x16x32_bf16 v[122:125], v[110:113], v[196:199], v[122:125]
	v_mfma_f32_16x16x32_bf16 v[106:109], v[90:93], v[200:203], v[106:109]
	v_mfma_f32_16x16x32_bf16 v[106:109], v[94:97], v[204:207], v[106:109]
	v_mfma_f32_16x16x32_bf16 v[98:101], v[102:105], v[200:203], v[98:101]
	v_mfma_f32_16x16x32_bf16 v[98:101], v[110:113], v[204:207], v[98:101]
	v_mfma_f32_16x16x32_bf16 v[78:81], v[90:93], v[208:211], v[78:81]
	v_mfma_f32_16x16x32_bf16 v[78:81], v[94:97], v[212:215], v[78:81]
	v_mfma_f32_16x16x32_bf16 v[74:77], v[102:105], v[208:211], v[74:77]
	v_mfma_f32_16x16x32_bf16 v[74:77], v[110:113], v[212:215], v[74:77]
	v_mfma_f32_16x16x32_bf16 v[134:137], v[146:149], v[178:181], v[134:137]
	v_mfma_f32_16x16x32_bf16 v[134:137], v[150:153], v[182:185], v[134:137]
	v_mfma_f32_16x16x32_bf16 v[130:133], v[154:157], v[178:181], v[130:133]
	v_mfma_f32_16x16x32_bf16 v[130:133], v[158:161], v[182:185], v[130:133]
	v_mfma_f32_16x16x32_bf16 v[118:121], v[146:149], v[192:195], v[118:121]
	v_mfma_f32_16x16x32_bf16 v[118:121], v[150:153], v[196:199], v[118:121]
	v_mfma_f32_16x16x32_bf16 v[114:117], v[154:157], v[192:195], v[114:117]
	v_mfma_f32_16x16x32_bf16 v[114:117], v[158:161], v[196:199], v[114:117]
	v_mfma_f32_16x16x32_bf16 v[86:89], v[146:149], v[200:203], v[86:89]
	v_mfma_f32_16x16x32_bf16 v[86:89], v[150:153], v[204:207], v[86:89]
	v_mfma_f32_16x16x32_bf16 v[82:85], v[154:157], v[200:203], v[82:85]
	v_mfma_f32_16x16x32_bf16 v[82:85], v[158:161], v[204:207], v[82:85]
	v_mfma_f32_16x16x32_bf16 v[70:73], v[146:149], v[208:211], v[70:73]
	v_mfma_f32_16x16x32_bf16 v[70:73], v[150:153], v[212:215], v[70:73]
	v_mfma_f32_16x16x32_bf16 v[66:69], v[154:157], v[208:211], v[66:69]
	v_mfma_f32_16x16x32_bf16 v[66:69], v[158:161], v[212:215], v[66:69]
	s_setprio 0
	s_barrier
	s_add_i32 s52, s45, s33
	s_mov_b32 m0, s52
	ds_read_b128 v[178:181], v190 offset:16384
	ds_read_b128 v[182:185], v190 offset:17408
	ds_read_b128 v[192:195], v190 offset:18432
	ds_read_b128 v[196:199], v190 offset:19456
	ds_read_b128 v[200:203], v190 offset:20480
	ds_read_b128 v[204:207], v190 offset:21504
	ds_read_b128 v[208:211], v190 offset:22528
	ds_read_b128 v[212:215], v190 offset:23552
	global_load_lds_dwordx4 v164, s[30:31]
	s_add_i32 m0, s52, 0x2000
	s_add_u32 s52, s30, 0x100000
	s_addc_u32 s53, s31, 0
	s_add_i32 s54, s46, s33
	global_load_lds_dwordx4 v168, s[30:31]
	s_mov_b32 m0, s54
	global_load_lds_dwordx4 v164, s[52:53]
	s_add_i32 m0, s54, 0x2000
	s_nop 0
	global_load_lds_dwordx4 v168, s[52:53]
	s_mov_b32 m0, s36
	s_nop 0
	global_load_lds_dwordx4 v162, s[34:35]
	s_mov_b32 m0, s37
	s_nop 0
	global_load_lds_dwordx4 v166, s[34:35]
	s_waitcnt vmcnt(8)
	s_waitcnt lgkmcnt(0)
	s_barrier
	s_setprio 1
	v_mfma_f32_16x16x32_bf16 v[62:65], v[90:93], v[178:181], v[62:65]
	v_mfma_f32_16x16x32_bf16 v[62:65], v[94:97], v[182:185], v[62:65]
	v_mfma_f32_16x16x32_bf16 v[58:61], v[102:105], v[178:181], v[58:61]
	v_mfma_f32_16x16x32_bf16 v[58:61], v[110:113], v[182:185], v[58:61]
	v_mfma_f32_16x16x32_bf16 v[46:49], v[90:93], v[192:195], v[46:49]
	v_mfma_f32_16x16x32_bf16 v[46:49], v[94:97], v[196:199], v[46:49]
	v_mfma_f32_16x16x32_bf16 v[42:45], v[102:105], v[192:195], v[42:45]
	v_mfma_f32_16x16x32_bf16 v[42:45], v[110:113], v[196:199], v[42:45]
	v_mfma_f32_16x16x32_bf16 v[30:33], v[90:93], v[200:203], v[30:33]
	v_mfma_f32_16x16x32_bf16 v[30:33], v[94:97], v[204:207], v[30:33]
	v_mfma_f32_16x16x32_bf16 v[26:29], v[102:105], v[200:203], v[26:29]
	v_mfma_f32_16x16x32_bf16 v[26:29], v[110:113], v[204:207], v[26:29]
	v_mfma_f32_16x16x32_bf16 v[14:17], v[90:93], v[208:211], v[14:17]
	v_mfma_f32_16x16x32_bf16 v[14:17], v[94:97], v[212:215], v[14:17]
	v_mfma_f32_16x16x32_bf16 v[10:13], v[102:105], v[208:211], v[10:13]
	v_mfma_f32_16x16x32_bf16 v[10:13], v[110:113], v[212:215], v[10:13]
	v_mfma_f32_16x16x32_bf16 v[54:57], v[146:149], v[178:181], v[54:57]
	v_mfma_f32_16x16x32_bf16 v[54:57], v[150:153], v[182:185], v[54:57]
	v_mfma_f32_16x16x32_bf16 v[50:53], v[154:157], v[178:181], v[50:53]
	v_mfma_f32_16x16x32_bf16 v[50:53], v[158:161], v[182:185], v[50:53]
	v_mfma_f32_16x16x32_bf16 v[38:41], v[146:149], v[192:195], v[38:41]
	v_mfma_f32_16x16x32_bf16 v[38:41], v[150:153], v[196:199], v[38:41]
	v_mfma_f32_16x16x32_bf16 v[34:37], v[154:157], v[192:195], v[34:37]
	v_mfma_f32_16x16x32_bf16 v[34:37], v[158:161], v[196:199], v[34:37]
	v_mfma_f32_16x16x32_bf16 v[22:25], v[146:149], v[200:203], v[22:25]
	v_mfma_f32_16x16x32_bf16 v[22:25], v[150:153], v[204:207], v[22:25]
	v_mfma_f32_16x16x32_bf16 v[18:21], v[154:157], v[200:203], v[18:21]
	v_mfma_f32_16x16x32_bf16 v[18:21], v[158:161], v[204:207], v[18:21]
	v_mfma_f32_16x16x32_bf16 v[6:9], v[146:149], v[208:211], v[6:9]
	v_mfma_f32_16x16x32_bf16 v[6:9], v[150:153], v[212:215], v[6:9]
	v_mfma_f32_16x16x32_bf16 v[2:5], v[154:157], v[208:211], v[2:5]
	v_mfma_f32_16x16x32_bf16 v[2:5], v[158:161], v[212:215], v[2:5]
	s_setprio 0
	s_barrier
	s_add_i32 s52, 0, 0x18000
	s_add_i32 s53, 0, 0x1c000
	v_add_u32_e32 v110, s52, v186
	v_add_u32_e32 v158, s53, v186
	ds_read_b128 v[90:93], v110
	ds_read_b128 v[94:97], v110 offset:1024
	ds_read_b128 v[102:105], v110 offset:2048
	ds_read_b128 v[110:113], v110 offset:3072
	ds_read_b128 v[146:149], v158
	ds_read_b128 v[150:153], v158 offset:1024
	ds_read_b128 v[154:157], v158 offset:2048
	ds_read_b128 v[158:161], v158 offset:3072
	s_add_u32 s98, s34, 0x80
	s_addc_u32 s99, s35, 0
	s_add_u32 s34, s34, 0x100000
	s_addc_u32 s35, s35, 0
	s_mov_b32 m0, s38
	ds_read_b128 v[178:181], v190 offset:32768
	ds_read_b128 v[182:185], v190 offset:33792
	ds_read_b128 v[192:195], v190 offset:34816
	ds_read_b128 v[196:199], v190 offset:35840
	ds_read_b128 v[200:203], v190 offset:36864
	ds_read_b128 v[204:207], v190 offset:37888
	ds_read_b128 v[208:211], v190 offset:38912
	ds_read_b128 v[212:215], v190 offset:39936
	global_load_lds_dwordx4 v162, s[34:35]
	s_mov_b32 m0, s39
	s_nop 0
	global_load_lds_dwordx4 v166, s[34:35]
	s_waitcnt vmcnt(8)
	s_waitcnt lgkmcnt(0)
	s_barrier
	s_setprio 1
	v_mfma_f32_16x16x32_bf16 v[142:145], v[90:93], v[178:181], v[142:145]
	v_mfma_f32_16x16x32_bf16 v[142:145], v[94:97], v[182:185], v[142:145]
	v_mfma_f32_16x16x32_bf16 v[138:141], v[102:105], v[178:181], v[138:141]
	v_mfma_f32_16x16x32_bf16 v[138:141], v[110:113], v[182:185], v[138:141]
	v_mfma_f32_16x16x32_bf16 v[126:129], v[90:93], v[192:195], v[126:129]
	v_mfma_f32_16x16x32_bf16 v[126:129], v[94:97], v[196:199], v[126:129]
	v_mfma_f32_16x16x32_bf16 v[122:125], v[102:105], v[192:195], v[122:125]
	v_mfma_f32_16x16x32_bf16 v[122:125], v[110:113], v[196:199], v[122:125]
	v_mfma_f32_16x16x32_bf16 v[106:109], v[90:93], v[200:203], v[106:109]
	v_mfma_f32_16x16x32_bf16 v[106:109], v[94:97], v[204:207], v[106:109]
	v_mfma_f32_16x16x32_bf16 v[98:101], v[102:105], v[200:203], v[98:101]
	v_mfma_f32_16x16x32_bf16 v[98:101], v[110:113], v[204:207], v[98:101]
	v_mfma_f32_16x16x32_bf16 v[78:81], v[90:93], v[208:211], v[78:81]
	v_mfma_f32_16x16x32_bf16 v[78:81], v[94:97], v[212:215], v[78:81]
	v_mfma_f32_16x16x32_bf16 v[74:77], v[102:105], v[208:211], v[74:77]
	v_mfma_f32_16x16x32_bf16 v[74:77], v[110:113], v[212:215], v[74:77]
	v_mfma_f32_16x16x32_bf16 v[134:137], v[146:149], v[178:181], v[134:137]
	v_mfma_f32_16x16x32_bf16 v[134:137], v[150:153], v[182:185], v[134:137]
	v_mfma_f32_16x16x32_bf16 v[130:133], v[154:157], v[178:181], v[130:133]
	v_mfma_f32_16x16x32_bf16 v[130:133], v[158:161], v[182:185], v[130:133]
	v_mfma_f32_16x16x32_bf16 v[118:121], v[146:149], v[192:195], v[118:121]
	v_mfma_f32_16x16x32_bf16 v[118:121], v[150:153], v[196:199], v[118:121]
	v_mfma_f32_16x16x32_bf16 v[114:117], v[154:157], v[192:195], v[114:117]
	v_mfma_f32_16x16x32_bf16 v[114:117], v[158:161], v[196:199], v[114:117]
	v_mfma_f32_16x16x32_bf16 v[86:89], v[146:149], v[200:203], v[86:89]
	v_mfma_f32_16x16x32_bf16 v[86:89], v[150:153], v[204:207], v[86:89]
	v_mfma_f32_16x16x32_bf16 v[82:85], v[154:157], v[200:203], v[82:85]
	v_mfma_f32_16x16x32_bf16 v[82:85], v[158:161], v[204:207], v[82:85]
	v_mfma_f32_16x16x32_bf16 v[70:73], v[146:149], v[208:211], v[70:73]
	v_mfma_f32_16x16x32_bf16 v[70:73], v[150:153], v[212:215], v[70:73]
	v_mfma_f32_16x16x32_bf16 v[66:69], v[154:157], v[208:211], v[66:69]
	v_mfma_f32_16x16x32_bf16 v[66:69], v[158:161], v[212:215], v[66:69]
	s_setprio 0
	s_barrier
	s_add_i32 s34, s52, s33
	s_mov_b32 m0, s34
	ds_read_b128 v[178:181], v190 offset:49152
	ds_read_b128 v[182:185], v190 offset:50176
	ds_read_b128 v[192:195], v190 offset:51200
	ds_read_b128 v[196:199], v190 offset:52224
	ds_read_b128 v[200:203], v190 offset:53248
	ds_read_b128 v[204:207], v190 offset:54272
	ds_read_b128 v[208:211], v190 offset:55296
	ds_read_b128 v[212:215], v190 offset:56320
	s_add_u32 s30, s30, 0x80
	s_addc_u32 s31, s31, 0
	global_load_lds_dwordx4 v164, s[30:31]
	s_add_i32 m0, s34, 0x2000
	s_add_i32 s34, s53, s33
	global_load_lds_dwordx4 v168, s[30:31]
	s_add_u32 s30, s30, 0x100000
	s_addc_u32 s31, s31, 0
	s_mov_b32 m0, s34
	s_nop 0
	global_load_lds_dwordx4 v164, s[30:31]
	s_add_i32 m0, s34, 0x2000
	s_nop 0
	global_load_lds_dwordx4 v168, s[30:31]
	s_mov_b32 m0, s43
	s_nop 0
	global_load_lds_dwordx4 v162, s[98:99]
	s_mov_b32 m0, s44
	s_nop 0
	global_load_lds_dwordx4 v166, s[98:99]
	s_waitcnt vmcnt(8)
	s_waitcnt lgkmcnt(0)
	s_barrier
	s_setprio 1
	v_mfma_f32_16x16x32_bf16 v[62:65], v[90:93], v[178:181], v[62:65]
	v_mfma_f32_16x16x32_bf16 v[62:65], v[94:97], v[182:185], v[62:65]
	v_mfma_f32_16x16x32_bf16 v[58:61], v[102:105], v[178:181], v[58:61]
	v_mfma_f32_16x16x32_bf16 v[58:61], v[110:113], v[182:185], v[58:61]
	v_mfma_f32_16x16x32_bf16 v[46:49], v[90:93], v[192:195], v[46:49]
	v_mfma_f32_16x16x32_bf16 v[46:49], v[94:97], v[196:199], v[46:49]
	v_mfma_f32_16x16x32_bf16 v[42:45], v[102:105], v[192:195], v[42:45]
	v_mfma_f32_16x16x32_bf16 v[42:45], v[110:113], v[196:199], v[42:45]
	v_mfma_f32_16x16x32_bf16 v[30:33], v[90:93], v[200:203], v[30:33]
	v_mfma_f32_16x16x32_bf16 v[30:33], v[94:97], v[204:207], v[30:33]
	v_mfma_f32_16x16x32_bf16 v[26:29], v[102:105], v[200:203], v[26:29]
	v_mfma_f32_16x16x32_bf16 v[26:29], v[110:113], v[204:207], v[26:29]
	v_mfma_f32_16x16x32_bf16 v[14:17], v[90:93], v[208:211], v[14:17]
	v_mfma_f32_16x16x32_bf16 v[14:17], v[94:97], v[212:215], v[14:17]
	v_mfma_f32_16x16x32_bf16 v[10:13], v[102:105], v[208:211], v[10:13]
	v_mfma_f32_16x16x32_bf16 v[10:13], v[110:113], v[212:215], v[10:13]
	v_mfma_f32_16x16x32_bf16 v[54:57], v[146:149], v[178:181], v[54:57]
	v_mfma_f32_16x16x32_bf16 v[54:57], v[150:153], v[182:185], v[54:57]
	v_mfma_f32_16x16x32_bf16 v[50:53], v[154:157], v[178:181], v[50:53]
	v_mfma_f32_16x16x32_bf16 v[50:53], v[158:161], v[182:185], v[50:53]
	v_mfma_f32_16x16x32_bf16 v[38:41], v[146:149], v[192:195], v[38:41]
	v_mfma_f32_16x16x32_bf16 v[38:41], v[150:153], v[196:199], v[38:41]
	v_mfma_f32_16x16x32_bf16 v[34:37], v[154:157], v[192:195], v[34:37]
	v_mfma_f32_16x16x32_bf16 v[34:37], v[158:161], v[196:199], v[34:37]
	v_mfma_f32_16x16x32_bf16 v[22:25], v[146:149], v[200:203], v[22:25]
	v_mfma_f32_16x16x32_bf16 v[22:25], v[150:153], v[204:207], v[22:25]
	v_mfma_f32_16x16x32_bf16 v[18:21], v[154:157], v[200:203], v[18:21]
	v_mfma_f32_16x16x32_bf16 v[18:21], v[158:161], v[204:207], v[18:21]
	v_mfma_f32_16x16x32_bf16 v[6:9], v[146:149], v[208:211], v[6:9]
	v_mfma_f32_16x16x32_bf16 v[6:9], v[150:153], v[212:215], v[6:9]
	v_mfma_f32_16x16x32_bf16 v[2:5], v[154:157], v[208:211], v[2:5]
	v_mfma_f32_16x16x32_bf16 v[2:5], v[158:161], v[212:215], v[2:5]
	s_setprio 0
	s_barrier
	s_add_i32 s51, s51, 2
	s_add_u32 s28, s28, 0x100
	s_addc_u32 s29, s29, 0
	s_add_u32 s49, s49, 0x100
	s_addc_u32 s50, s50, 0
	s_cmp_gt_u32 s51, 61
	s_cbranch_scc0 .LBB0_941
	s_and_b64 vcc, exec, s[16:17]
	s_cbranch_vccz .LBB0_944
	s_barrier

.LBB0_1153:
	v_add_u32_e32 v146, s78, v187
	v_add_u32_e32 v162, s79, v187
	s_add_u32 s98, s46, s10
	s_addc_u32 s99, s47, s11
	s_add_u32 s98, s98, 0x100080
	s_addc_u32 s99, s99, 0
	s_add_u32 s56, s46, s10
	ds_read_b128 v[134:137], v146
	ds_read_b128 v[138:141], v146 offset:1024
	ds_read_b128 v[142:145], v146 offset:2048
	ds_read_b128 v[146:149], v146 offset:3072
	ds_read_b128 v[150:153], v162
	ds_read_b128 v[154:157], v162 offset:1024
	ds_read_b128 v[158:161], v162 offset:2048
	ds_read_b128 v[162:165], v162 offset:3072
	s_addc_u32 s57, s47, s11
	s_add_u32 s56, s56, 0x100
	s_addc_u32 s57, s57, 0
	s_add_u32 s84, s33, s10
	s_addc_u32 s85, s72, s11
	s_cmpk_eq_i32 s10, 0x1f00
	s_cselect_b32 s59, s29, s57
	s_cselect_b32 s58, s45, s56
	s_cselect_b32 s57, s43, s85
	s_cselect_b32 s56, s73, s84
	s_add_i32 m0, s64, 0xc000
	ds_read_b128 v[166:169], v230
	ds_read_b128 v[170:173], v230 offset:1024
	ds_read_b128 v[174:177], v230 offset:2048
	ds_read_b128 v[202:205], v230 offset:3072
	ds_read_b128 v[206:209], v230 offset:4096
	ds_read_b128 v[210:213], v230 offset:5120
	ds_read_b128 v[214:217], v230 offset:6144
	ds_read_b128 v[218:221], v230 offset:7168
	global_load_lds_dwordx4 v178, s[98:99]
	s_add_i32 m0, s64, 0xe000
	s_nop 0
	global_load_lds_dwordx4 v182, s[98:99]
	s_waitcnt vmcnt(8)
	s_waitcnt lgkmcnt(0)
	s_barrier
	s_setprio 1
	v_mfma_f32_16x16x32_bf16 v[2:5], v[134:137], v[166:169], v[2:5]
	v_mfma_f32_16x16x32_bf16 v[2:5], v[138:141], v[170:173], v[2:5]
	v_mfma_f32_16x16x32_bf16 v[126:129], v[142:145], v[166:169], v[126:129]
	v_mfma_f32_16x16x32_bf16 v[126:129], v[146:149], v[170:173], v[126:129]
	v_mfma_f32_16x16x32_bf16 v[122:125], v[134:137], v[174:177], v[122:125]
	v_mfma_f32_16x16x32_bf16 v[122:125], v[138:141], v[202:205], v[122:125]
	v_mfma_f32_16x16x32_bf16 v[118:121], v[142:145], v[174:177], v[118:121]
	v_mfma_f32_16x16x32_bf16 v[118:121], v[146:149], v[202:205], v[118:121]
	v_mfma_f32_16x16x32_bf16 v[114:117], v[134:137], v[206:209], v[114:117]
	v_mfma_f32_16x16x32_bf16 v[114:117], v[138:141], v[210:213], v[114:117]
	v_mfma_f32_16x16x32_bf16 v[110:113], v[142:145], v[206:209], v[110:113]
	v_mfma_f32_16x16x32_bf16 v[110:113], v[146:149], v[210:213], v[110:113]
	v_mfma_f32_16x16x32_bf16 v[106:109], v[134:137], v[214:217], v[106:109]
	v_mfma_f32_16x16x32_bf16 v[106:109], v[138:141], v[218:221], v[106:109]
	v_mfma_f32_16x16x32_bf16 v[102:105], v[142:145], v[214:217], v[102:105]
	v_mfma_f32_16x16x32_bf16 v[102:105], v[146:149], v[218:221], v[102:105]
	v_mfma_f32_16x16x32_bf16 v[98:101], v[150:153], v[166:169], v[98:101]
	v_mfma_f32_16x16x32_bf16 v[98:101], v[154:157], v[170:173], v[98:101]
	v_mfma_f32_16x16x32_bf16 v[94:97], v[158:161], v[166:169], v[94:97]
	v_mfma_f32_16x16x32_bf16 v[94:97], v[162:165], v[170:173], v[94:97]
	v_mfma_f32_16x16x32_bf16 v[90:93], v[150:153], v[174:177], v[90:93]
	v_mfma_f32_16x16x32_bf16 v[90:93], v[154:157], v[202:205], v[90:93]
	v_mfma_f32_16x16x32_bf16 v[86:89], v[158:161], v[174:177], v[86:89]
	v_mfma_f32_16x16x32_bf16 v[86:89], v[162:165], v[202:205], v[86:89]
	v_mfma_f32_16x16x32_bf16 v[82:85], v[150:153], v[206:209], v[82:85]
	v_mfma_f32_16x16x32_bf16 v[82:85], v[154:157], v[210:213], v[82:85]
	v_mfma_f32_16x16x32_bf16 v[78:81], v[158:161], v[206:209], v[78:81]
	v_mfma_f32_16x16x32_bf16 v[78:81], v[162:165], v[210:213], v[78:81]
	v_mfma_f32_16x16x32_bf16 v[74:77], v[150:153], v[214:217], v[74:77]
	v_mfma_f32_16x16x32_bf16 v[74:77], v[154:157], v[218:221], v[74:77]
	v_mfma_f32_16x16x32_bf16 v[70:73], v[158:161], v[214:217], v[70:73]
	v_mfma_f32_16x16x32_bf16 v[70:73], v[162:165], v[218:221], v[70:73]
	s_setprio 0
	s_barrier
	s_add_i32 s84, s78, s63
	s_mov_b32 m0, s84
	ds_read_b128 v[166:169], v230 offset:16384
	ds_read_b128 v[170:173], v230 offset:17408
	ds_read_b128 v[174:177], v230 offset:18432
	ds_read_b128 v[202:205], v230 offset:19456
	ds_read_b128 v[206:209], v230 offset:20480
	ds_read_b128 v[210:213], v230 offset:21504
	ds_read_b128 v[214:217], v230 offset:22528
	ds_read_b128 v[218:221], v230 offset:23552
	global_load_lds_dwordx4 v180, s[56:57]
	s_add_i32 m0, s84, 0x2000
	s_add_u32 s84, s56, 0x100000
	s_addc_u32 s85, s57, 0
	s_add_i32 s86, s79, s63
	global_load_lds_dwordx4 v184, s[56:57]
	s_mov_b32 m0, s86
	s_nop 0
	global_load_lds_dwordx4 v180, s[84:85]
	s_add_i32 m0, s86, 0x2000
	s_nop 0
	global_load_lds_dwordx4 v184, s[84:85]
	s_mov_b32 m0, s64
	s_nop 0
	global_load_lds_dwordx4 v178, s[58:59]
	s_mov_b32 m0, s65
	s_nop 0
	global_load_lds_dwordx4 v182, s[58:59]
	s_waitcnt vmcnt(8)
	s_waitcnt lgkmcnt(0)
	s_barrier
	s_setprio 1
	v_mfma_f32_16x16x32_bf16 v[66:69], v[134:137], v[166:169], v[66:69]
	v_mfma_f32_16x16x32_bf16 v[66:69], v[138:141], v[170:173], v[66:69]
	v_mfma_f32_16x16x32_bf16 v[62:65], v[142:145], v[166:169], v[62:65]
	v_mfma_f32_16x16x32_bf16 v[62:65], v[146:149], v[170:173], v[62:65]
	v_mfma_f32_16x16x32_bf16 v[58:61], v[134:137], v[174:177], v[58:61]
	v_mfma_f32_16x16x32_bf16 v[58:61], v[138:141], v[202:205], v[58:61]
	v_mfma_f32_16x16x32_bf16 v[54:57], v[142:145], v[174:177], v[54:57]
	v_mfma_f32_16x16x32_bf16 v[54:57], v[146:149], v[202:205], v[54:57]
	v_mfma_f32_16x16x32_bf16 v[50:53], v[134:137], v[206:209], v[50:53]
	v_mfma_f32_16x16x32_bf16 v[50:53], v[138:141], v[210:213], v[50:53]
	v_mfma_f32_16x16x32_bf16 v[46:49], v[142:145], v[206:209], v[46:49]
	v_mfma_f32_16x16x32_bf16 v[46:49], v[146:149], v[210:213], v[46:49]
	v_mfma_f32_16x16x32_bf16 v[42:45], v[134:137], v[214:217], v[42:45]
	v_mfma_f32_16x16x32_bf16 v[42:45], v[138:141], v[218:221], v[42:45]
	v_mfma_f32_16x16x32_bf16 v[38:41], v[142:145], v[214:217], v[38:41]
	v_mfma_f32_16x16x32_bf16 v[38:41], v[146:149], v[218:221], v[38:41]
	v_mfma_f32_16x16x32_bf16 v[34:37], v[150:153], v[166:169], v[34:37]
	v_mfma_f32_16x16x32_bf16 v[34:37], v[154:157], v[170:173], v[34:37]
	v_mfma_f32_16x16x32_bf16 v[30:33], v[158:161], v[166:169], v[30:33]
	v_mfma_f32_16x16x32_bf16 v[30:33], v[162:165], v[170:173], v[30:33]
	v_mfma_f32_16x16x32_bf16 v[26:29], v[150:153], v[174:177], v[26:29]
	v_mfma_f32_16x16x32_bf16 v[26:29], v[154:157], v[202:205], v[26:29]
	v_mfma_f32_16x16x32_bf16 v[22:25], v[158:161], v[174:177], v[22:25]
	v_mfma_f32_16x16x32_bf16 v[22:25], v[162:165], v[202:205], v[22:25]
	v_mfma_f32_16x16x32_bf16 v[18:21], v[150:153], v[206:209], v[18:21]
	v_mfma_f32_16x16x32_bf16 v[18:21], v[154:157], v[210:213], v[18:21]
	v_mfma_f32_16x16x32_bf16 v[14:17], v[158:161], v[206:209], v[14:17]
	v_mfma_f32_16x16x32_bf16 v[14:17], v[162:165], v[210:213], v[14:17]
	v_mfma_f32_16x16x32_bf16 v[10:13], v[150:153], v[214:217], v[10:13]
	v_mfma_f32_16x16x32_bf16 v[10:13], v[154:157], v[218:221], v[10:13]
	v_mfma_f32_16x16x32_bf16 v[6:9], v[158:161], v[214:217], v[6:9]
	v_mfma_f32_16x16x32_bf16 v[6:9], v[162:165], v[218:221], v[6:9]
	s_setprio 0
	s_barrier
	s_add_i32 s84, 0, 0x18000
	s_add_i32 s85, 0, 0x1c000
	v_add_u32_e32 v146, s84, v187
	v_add_u32_e32 v162, s85, v187
	ds_read_b128 v[134:137], v146
	ds_read_b128 v[138:141], v146 offset:1024
	ds_read_b128 v[142:145], v146 offset:2048
	ds_read_b128 v[146:149], v146 offset:3072
	ds_read_b128 v[150:153], v162
	ds_read_b128 v[154:157], v162 offset:1024
	ds_read_b128 v[158:161], v162 offset:2048
	ds_read_b128 v[162:165], v162 offset:3072
	s_add_u32 s100, s58, 0x80
	s_addc_u32 s101, s59, 0
	s_add_u32 s58, s58, 0x100000
	s_addc_u32 s59, s59, 0
	s_mov_b32 m0, s67
	ds_read_b128 v[166:169], v230 offset:32768
	ds_read_b128 v[170:173], v230 offset:33792
	ds_read_b128 v[174:177], v230 offset:34816
	ds_read_b128 v[202:205], v230 offset:35840
	ds_read_b128 v[206:209], v230 offset:36864
	ds_read_b128 v[210:213], v230 offset:37888
	ds_read_b128 v[214:217], v230 offset:38912
	ds_read_b128 v[218:221], v230 offset:39936
	global_load_lds_dwordx4 v178, s[58:59]
	s_mov_b32 m0, s68
	s_nop 0
	global_load_lds_dwordx4 v182, s[58:59]
	s_waitcnt vmcnt(8)
	s_waitcnt lgkmcnt(0)
	s_barrier
	s_setprio 1
	v_mfma_f32_16x16x32_bf16 v[2:5], v[134:137], v[166:169], v[2:5]
	v_mfma_f32_16x16x32_bf16 v[2:5], v[138:141], v[170:173], v[2:5]
	v_mfma_f32_16x16x32_bf16 v[126:129], v[142:145], v[166:169], v[126:129]
	v_mfma_f32_16x16x32_bf16 v[126:129], v[146:149], v[170:173], v[126:129]
	v_mfma_f32_16x16x32_bf16 v[122:125], v[134:137], v[174:177], v[122:125]
	v_mfma_f32_16x16x32_bf16 v[122:125], v[138:141], v[202:205], v[122:125]
	v_mfma_f32_16x16x32_bf16 v[118:121], v[142:145], v[174:177], v[118:121]
	v_mfma_f32_16x16x32_bf16 v[118:121], v[146:149], v[202:205], v[118:121]
	v_mfma_f32_16x16x32_bf16 v[114:117], v[134:137], v[206:209], v[114:117]
	v_mfma_f32_16x16x32_bf16 v[114:117], v[138:141], v[210:213], v[114:117]
	v_mfma_f32_16x16x32_bf16 v[110:113], v[142:145], v[206:209], v[110:113]
	v_mfma_f32_16x16x32_bf16 v[110:113], v[146:149], v[210:213], v[110:113]
	v_mfma_f32_16x16x32_bf16 v[106:109], v[134:137], v[214:217], v[106:109]
	v_mfma_f32_16x16x32_bf16 v[106:109], v[138:141], v[218:221], v[106:109]
	v_mfma_f32_16x16x32_bf16 v[102:105], v[142:145], v[214:217], v[102:105]
	v_mfma_f32_16x16x32_bf16 v[102:105], v[146:149], v[218:221], v[102:105]
	v_mfma_f32_16x16x32_bf16 v[98:101], v[150:153], v[166:169], v[98:101]
	v_mfma_f32_16x16x32_bf16 v[98:101], v[154:157], v[170:173], v[98:101]
	v_mfma_f32_16x16x32_bf16 v[94:97], v[158:161], v[166:169], v[94:97]
	v_mfma_f32_16x16x32_bf16 v[94:97], v[162:165], v[170:173], v[94:97]
	v_mfma_f32_16x16x32_bf16 v[90:93], v[150:153], v[174:177], v[90:93]
	v_mfma_f32_16x16x32_bf16 v[90:93], v[154:157], v[202:205], v[90:93]
	v_mfma_f32_16x16x32_bf16 v[86:89], v[158:161], v[174:177], v[86:89]
	v_mfma_f32_16x16x32_bf16 v[86:89], v[162:165], v[202:205], v[86:89]
	v_mfma_f32_16x16x32_bf16 v[82:85], v[150:153], v[206:209], v[82:85]
	v_mfma_f32_16x16x32_bf16 v[82:85], v[154:157], v[210:213], v[82:85]
	v_mfma_f32_16x16x32_bf16 v[78:81], v[158:161], v[206:209], v[78:81]
	v_mfma_f32_16x16x32_bf16 v[78:81], v[162:165], v[210:213], v[78:81]
	v_mfma_f32_16x16x32_bf16 v[74:77], v[150:153], v[214:217], v[74:77]
	v_mfma_f32_16x16x32_bf16 v[74:77], v[154:157], v[218:221], v[74:77]
	v_mfma_f32_16x16x32_bf16 v[70:73], v[158:161], v[214:217], v[70:73]
	v_mfma_f32_16x16x32_bf16 v[70:73], v[162:165], v[218:221], v[70:73]
	s_setprio 0
	s_barrier
	s_add_i32 s58, s84, s63
	s_add_u32 s98, s56, 0x80
	s_addc_u32 s99, s57, 0
	s_mov_b32 m0, s58
	ds_read_b128 v[166:169], v230 offset:49152
	ds_read_b128 v[170:173], v230 offset:50176
	ds_read_b128 v[174:177], v230 offset:51200
	ds_read_b128 v[202:205], v230 offset:52224
	ds_read_b128 v[206:209], v230 offset:53248
	ds_read_b128 v[210:213], v230 offset:54272
	ds_read_b128 v[214:217], v230 offset:55296
	ds_read_b128 v[218:221], v230 offset:56320
	global_load_lds_dwordx4 v180, s[98:99]
	s_add_i32 m0, s58, 0x2000
	s_add_u32 s56, s56, 0x100080
	s_addc_u32 s57, s57, 0
	s_add_i32 s58, s85, s63
	global_load_lds_dwordx4 v184, s[98:99]
	s_mov_b32 m0, s58
	s_nop 0
	global_load_lds_dwordx4 v180, s[56:57]
	s_add_i32 m0, s58, 0x2000
	s_nop 0
	global_load_lds_dwordx4 v184, s[56:57]
	s_mov_b32 m0, s74
	s_nop 0
	global_load_lds_dwordx4 v178, s[100:101]
	s_mov_b32 m0, s75
	s_nop 0
	global_load_lds_dwordx4 v182, s[100:101]
	s_waitcnt vmcnt(8)
	s_waitcnt lgkmcnt(0)
	s_barrier
	s_setprio 1
	v_mfma_f32_16x16x32_bf16 v[66:69], v[134:137], v[166:169], v[66:69]
	v_mfma_f32_16x16x32_bf16 v[66:69], v[138:141], v[170:173], v[66:69]
	v_mfma_f32_16x16x32_bf16 v[62:65], v[142:145], v[166:169], v[62:65]
	v_mfma_f32_16x16x32_bf16 v[62:65], v[146:149], v[170:173], v[62:65]
	v_mfma_f32_16x16x32_bf16 v[58:61], v[134:137], v[174:177], v[58:61]
	v_mfma_f32_16x16x32_bf16 v[58:61], v[138:141], v[202:205], v[58:61]
	v_mfma_f32_16x16x32_bf16 v[54:57], v[142:145], v[174:177], v[54:57]
	v_mfma_f32_16x16x32_bf16 v[54:57], v[146:149], v[202:205], v[54:57]
	v_mfma_f32_16x16x32_bf16 v[50:53], v[134:137], v[206:209], v[50:53]
	v_mfma_f32_16x16x32_bf16 v[50:53], v[138:141], v[210:213], v[50:53]
	v_mfma_f32_16x16x32_bf16 v[46:49], v[142:145], v[206:209], v[46:49]
	v_mfma_f32_16x16x32_bf16 v[46:49], v[146:149], v[210:213], v[46:49]
	v_mfma_f32_16x16x32_bf16 v[42:45], v[134:137], v[214:217], v[42:45]
	v_mfma_f32_16x16x32_bf16 v[42:45], v[138:141], v[218:221], v[42:45]
	v_mfma_f32_16x16x32_bf16 v[38:41], v[142:145], v[214:217], v[38:41]
	v_mfma_f32_16x16x32_bf16 v[38:41], v[146:149], v[218:221], v[38:41]
	v_mfma_f32_16x16x32_bf16 v[34:37], v[150:153], v[166:169], v[34:37]
	v_mfma_f32_16x16x32_bf16 v[34:37], v[154:157], v[170:173], v[34:37]
	v_mfma_f32_16x16x32_bf16 v[30:33], v[158:161], v[166:169], v[30:33]
	v_mfma_f32_16x16x32_bf16 v[30:33], v[162:165], v[170:173], v[30:33]
	v_mfma_f32_16x16x32_bf16 v[26:29], v[150:153], v[174:177], v[26:29]
	v_mfma_f32_16x16x32_bf16 v[26:29], v[154:157], v[202:205], v[26:29]
	v_mfma_f32_16x16x32_bf16 v[22:25], v[158:161], v[174:177], v[22:25]
	v_mfma_f32_16x16x32_bf16 v[22:25], v[162:165], v[202:205], v[22:25]
	v_mfma_f32_16x16x32_bf16 v[18:21], v[150:153], v[206:209], v[18:21]
	v_mfma_f32_16x16x32_bf16 v[18:21], v[154:157], v[210:213], v[18:21]
	v_mfma_f32_16x16x32_bf16 v[14:17], v[158:161], v[206:209], v[14:17]
	v_mfma_f32_16x16x32_bf16 v[14:17], v[162:165], v[210:213], v[14:17]
	v_mfma_f32_16x16x32_bf16 v[10:13], v[150:153], v[214:217], v[10:13]
	v_mfma_f32_16x16x32_bf16 v[10:13], v[154:157], v[218:221], v[10:13]
	v_mfma_f32_16x16x32_bf16 v[6:9], v[158:161], v[214:217], v[6:9]
	v_mfma_f32_16x16x32_bf16 v[6:9], v[162:165], v[218:221], v[6:9]
	s_setprio 0
	s_barrier
	s_add_i32 s83, s83, 2
	s_add_u32 s10, s10, 0x100
	s_addc_u32 s11, s11, 0
	s_cmp_gt_u32 s83, 61
	s_cbranch_scc0 .LBB0_1153
	s_and_b64 vcc, exec, s[36:37]
	s_cbranch_vccz .LBB0_1156
	s_barrier

.LBB0_1325:
	ds_read_b128 v[130:133], v176
	ds_read_b128 v[134:137], v176 offset:1024
	ds_read_b128 v[138:141], v176 offset:2048
	ds_read_b128 v[142:145], v176 offset:3072
	ds_read_b128 v[146:149], v177
	ds_read_b128 v[166:169], v177 offset:1024
	ds_read_b128 v[170:173], v177 offset:2048
	ds_read_b128 v[180:183], v177 offset:3072
	s_add_u32 s26, s24, 0xffd50080
	s_addc_u32 s27, s25, -1
	s_cmpk_eq_i32 s49, 0xa8
	s_cselect_b32 s29, s5, s27
	s_cselect_b32 s28, s4, s26
	s_cselect_b32 s27, s23, s48
	s_cselect_b32 s26, s22, s47
	s_add_i32 m0, s33, 0xc000
	ds_read_b128 v[184:187], v178
	ds_read_b128 v[188:191], v178 offset:1024
	ds_read_b128 v[192:195], v178 offset:2048
	ds_read_b128 v[196:199], v178 offset:3072
	ds_read_b128 v[200:203], v178 offset:4096
	ds_read_b128 v[204:207], v178 offset:5120
	ds_read_b128 v[208:211], v178 offset:6144
	ds_read_b128 v[212:215], v178 offset:7168
	global_load_lds_dwordx4 v158, s[24:25]
	s_add_i32 m0, s33, 0xe000
	s_nop 0
	global_load_lds_dwordx4 v160, s[24:25]
	s_waitcnt vmcnt(8)
	s_waitcnt lgkmcnt(0)
	s_barrier
	s_setprio 1
	v_mfma_f32_16x16x32_bf16 v[126:129], v[130:133], v[184:187], v[126:129]
	v_mfma_f32_16x16x32_bf16 v[126:129], v[134:137], v[188:191], v[126:129]
	v_mfma_f32_16x16x32_bf16 v[122:125], v[138:141], v[184:187], v[122:125]
	v_mfma_f32_16x16x32_bf16 v[122:125], v[142:145], v[188:191], v[122:125]
	v_mfma_f32_16x16x32_bf16 v[110:113], v[130:133], v[192:195], v[110:113]
	v_mfma_f32_16x16x32_bf16 v[110:113], v[134:137], v[196:199], v[110:113]
	v_mfma_f32_16x16x32_bf16 v[106:109], v[138:141], v[192:195], v[106:109]
	v_mfma_f32_16x16x32_bf16 v[106:109], v[142:145], v[196:199], v[106:109]
	v_mfma_f32_16x16x32_bf16 v[94:97], v[130:133], v[200:203], v[94:97]
	v_mfma_f32_16x16x32_bf16 v[94:97], v[134:137], v[204:207], v[94:97]
	v_mfma_f32_16x16x32_bf16 v[90:93], v[138:141], v[200:203], v[90:93]
	v_mfma_f32_16x16x32_bf16 v[90:93], v[142:145], v[204:207], v[90:93]
	v_mfma_f32_16x16x32_bf16 v[78:81], v[130:133], v[208:211], v[78:81]
	v_mfma_f32_16x16x32_bf16 v[78:81], v[134:137], v[212:215], v[78:81]
	v_mfma_f32_16x16x32_bf16 v[74:77], v[138:141], v[208:211], v[74:77]
	v_mfma_f32_16x16x32_bf16 v[74:77], v[142:145], v[212:215], v[74:77]
	v_mfma_f32_16x16x32_bf16 v[118:121], v[146:149], v[184:187], v[118:121]
	v_mfma_f32_16x16x32_bf16 v[118:121], v[166:169], v[188:191], v[118:121]
	v_mfma_f32_16x16x32_bf16 v[114:117], v[170:173], v[184:187], v[114:117]
	v_mfma_f32_16x16x32_bf16 v[114:117], v[180:183], v[188:191], v[114:117]
	v_mfma_f32_16x16x32_bf16 v[102:105], v[146:149], v[192:195], v[102:105]
	v_mfma_f32_16x16x32_bf16 v[102:105], v[166:169], v[196:199], v[102:105]
	v_mfma_f32_16x16x32_bf16 v[98:101], v[170:173], v[192:195], v[98:101]
	v_mfma_f32_16x16x32_bf16 v[98:101], v[180:183], v[196:199], v[98:101]
	v_mfma_f32_16x16x32_bf16 v[86:89], v[146:149], v[200:203], v[86:89]
	v_mfma_f32_16x16x32_bf16 v[86:89], v[166:169], v[204:207], v[86:89]
	v_mfma_f32_16x16x32_bf16 v[82:85], v[170:173], v[200:203], v[82:85]
	v_mfma_f32_16x16x32_bf16 v[82:85], v[180:183], v[204:207], v[82:85]
	v_mfma_f32_16x16x32_bf16 v[70:73], v[146:149], v[208:211], v[70:73]
	v_mfma_f32_16x16x32_bf16 v[70:73], v[166:169], v[212:215], v[70:73]
	v_mfma_f32_16x16x32_bf16 v[66:69], v[170:173], v[208:211], v[66:69]
	v_mfma_f32_16x16x32_bf16 v[66:69], v[180:183], v[212:215], v[66:69]
	s_setprio 0
	s_barrier
	s_add_i32 s50, s41, s31
	s_mov_b32 m0, s50
	ds_read_b128 v[184:187], v178 offset:16384
	ds_read_b128 v[188:191], v178 offset:17408
	ds_read_b128 v[192:195], v178 offset:18432
	ds_read_b128 v[196:199], v178 offset:19456
	ds_read_b128 v[200:203], v178 offset:20480
	ds_read_b128 v[204:207], v178 offset:21504
	ds_read_b128 v[208:211], v178 offset:22528
	ds_read_b128 v[212:215], v178 offset:23552
	global_load_lds_dwordx4 v152, s[26:27]
	s_add_i32 m0, s50, 0x2000
	s_add_u32 s50, s26, 0x2b0000
	s_addc_u32 s51, s27, 0
	s_add_i32 s52, s42, s31
	global_load_lds_dwordx4 v156, s[26:27]
	s_mov_b32 m0, s52
	global_load_lds_dwordx4 v152, s[50:51]
	s_add_i32 m0, s52, 0x2000
	s_nop 0
	global_load_lds_dwordx4 v156, s[50:51]
	s_mov_b32 m0, s33
	s_nop 0
	global_load_lds_dwordx4 v150, s[28:29]
	s_mov_b32 m0, s34
	s_nop 0
	global_load_lds_dwordx4 v154, s[28:29]
	s_waitcnt vmcnt(8)
	s_waitcnt lgkmcnt(0)
	s_barrier
	s_setprio 1
	v_mfma_f32_16x16x32_bf16 v[62:65], v[130:133], v[184:187], v[62:65]
	v_mfma_f32_16x16x32_bf16 v[62:65], v[134:137], v[188:191], v[62:65]
	v_mfma_f32_16x16x32_bf16 v[58:61], v[138:141], v[184:187], v[58:61]
	v_mfma_f32_16x16x32_bf16 v[58:61], v[142:145], v[188:191], v[58:61]
	v_mfma_f32_16x16x32_bf16 v[46:49], v[130:133], v[192:195], v[46:49]
	v_mfma_f32_16x16x32_bf16 v[46:49], v[134:137], v[196:199], v[46:49]
	v_mfma_f32_16x16x32_bf16 v[42:45], v[138:141], v[192:195], v[42:45]
	v_mfma_f32_16x16x32_bf16 v[42:45], v[142:145], v[196:199], v[42:45]
	v_mfma_f32_16x16x32_bf16 v[30:33], v[130:133], v[200:203], v[30:33]
	v_mfma_f32_16x16x32_bf16 v[30:33], v[134:137], v[204:207], v[30:33]
	v_mfma_f32_16x16x32_bf16 v[26:29], v[138:141], v[200:203], v[26:29]
	v_mfma_f32_16x16x32_bf16 v[26:29], v[142:145], v[204:207], v[26:29]
	v_mfma_f32_16x16x32_bf16 v[14:17], v[130:133], v[208:211], v[14:17]
	v_mfma_f32_16x16x32_bf16 v[14:17], v[134:137], v[212:215], v[14:17]
	v_mfma_f32_16x16x32_bf16 v[10:13], v[138:141], v[208:211], v[10:13]
	v_mfma_f32_16x16x32_bf16 v[10:13], v[142:145], v[212:215], v[10:13]
	v_mfma_f32_16x16x32_bf16 v[54:57], v[146:149], v[184:187], v[54:57]
	v_mfma_f32_16x16x32_bf16 v[54:57], v[166:169], v[188:191], v[54:57]
	v_mfma_f32_16x16x32_bf16 v[50:53], v[170:173], v[184:187], v[50:53]
	v_mfma_f32_16x16x32_bf16 v[50:53], v[180:183], v[188:191], v[50:53]
	v_mfma_f32_16x16x32_bf16 v[38:41], v[146:149], v[192:195], v[38:41]
	v_mfma_f32_16x16x32_bf16 v[38:41], v[166:169], v[196:199], v[38:41]
	v_mfma_f32_16x16x32_bf16 v[34:37], v[170:173], v[192:195], v[34:37]
	v_mfma_f32_16x16x32_bf16 v[34:37], v[180:183], v[196:199], v[34:37]
	v_mfma_f32_16x16x32_bf16 v[22:25], v[146:149], v[200:203], v[22:25]
	v_mfma_f32_16x16x32_bf16 v[22:25], v[166:169], v[204:207], v[22:25]
	v_mfma_f32_16x16x32_bf16 v[18:21], v[170:173], v[200:203], v[18:21]
	v_mfma_f32_16x16x32_bf16 v[18:21], v[180:183], v[204:207], v[18:21]
	v_mfma_f32_16x16x32_bf16 v[6:9], v[146:149], v[208:211], v[6:9]
	v_mfma_f32_16x16x32_bf16 v[6:9], v[166:169], v[212:215], v[6:9]
	v_mfma_f32_16x16x32_bf16 v[2:5], v[170:173], v[208:211], v[2:5]
	v_mfma_f32_16x16x32_bf16 v[2:5], v[180:183], v[212:215], v[2:5]
	s_setprio 0
	s_barrier
	s_add_i32 s50, 0, 0x18000
	s_add_i32 s51, 0, 0x1c000
	v_add_u32_e32 v142, s50, v174
	v_add_u32_e32 v179, s51, v174
	ds_read_b128 v[130:133], v142
	ds_read_b128 v[134:137], v142 offset:1024
	ds_read_b128 v[138:141], v142 offset:2048
	ds_read_b128 v[142:145], v142 offset:3072
	ds_read_b128 v[146:149], v179
	ds_read_b128 v[166:169], v179 offset:1024
	ds_read_b128 v[170:173], v179 offset:2048
	ds_read_b128 v[180:183], v179 offset:3072
	s_add_u32 s98, s28, 0x80
	s_addc_u32 s99, s29, 0
	s_add_u32 s28, s28, 0x2b0000
	s_addc_u32 s29, s29, 0
	s_mov_b32 m0, s35
	ds_read_b128 v[184:187], v178 offset:32768
	ds_read_b128 v[188:191], v178 offset:33792
	ds_read_b128 v[192:195], v178 offset:34816
	ds_read_b128 v[196:199], v178 offset:35840
	ds_read_b128 v[200:203], v178 offset:36864
	ds_read_b128 v[204:207], v178 offset:37888
	ds_read_b128 v[208:211], v178 offset:38912
	ds_read_b128 v[212:215], v178 offset:39936
	global_load_lds_dwordx4 v150, s[28:29]
	s_mov_b32 m0, s36
	s_nop 0
	global_load_lds_dwordx4 v154, s[28:29]
	s_waitcnt vmcnt(8)
	s_waitcnt lgkmcnt(0)
	s_barrier
	s_setprio 1
	v_mfma_f32_16x16x32_bf16 v[126:129], v[130:133], v[184:187], v[126:129]
	v_mfma_f32_16x16x32_bf16 v[126:129], v[134:137], v[188:191], v[126:129]
	v_mfma_f32_16x16x32_bf16 v[122:125], v[138:141], v[184:187], v[122:125]
	v_mfma_f32_16x16x32_bf16 v[122:125], v[142:145], v[188:191], v[122:125]
	v_mfma_f32_16x16x32_bf16 v[110:113], v[130:133], v[192:195], v[110:113]
	v_mfma_f32_16x16x32_bf16 v[110:113], v[134:137], v[196:199], v[110:113]
	v_mfma_f32_16x16x32_bf16 v[106:109], v[138:141], v[192:195], v[106:109]
	v_mfma_f32_16x16x32_bf16 v[106:109], v[142:145], v[196:199], v[106:109]
	v_mfma_f32_16x16x32_bf16 v[94:97], v[130:133], v[200:203], v[94:97]
	v_mfma_f32_16x16x32_bf16 v[94:97], v[134:137], v[204:207], v[94:97]
	v_mfma_f32_16x16x32_bf16 v[90:93], v[138:141], v[200:203], v[90:93]
	v_mfma_f32_16x16x32_bf16 v[90:93], v[142:145], v[204:207], v[90:93]
	v_mfma_f32_16x16x32_bf16 v[78:81], v[130:133], v[208:211], v[78:81]
	v_mfma_f32_16x16x32_bf16 v[78:81], v[134:137], v[212:215], v[78:81]
	v_mfma_f32_16x16x32_bf16 v[74:77], v[138:141], v[208:211], v[74:77]
	v_mfma_f32_16x16x32_bf16 v[74:77], v[142:145], v[212:215], v[74:77]
	v_mfma_f32_16x16x32_bf16 v[118:121], v[146:149], v[184:187], v[118:121]
	v_mfma_f32_16x16x32_bf16 v[118:121], v[166:169], v[188:191], v[118:121]
	v_mfma_f32_16x16x32_bf16 v[114:117], v[170:173], v[184:187], v[114:117]
	v_mfma_f32_16x16x32_bf16 v[114:117], v[180:183], v[188:191], v[114:117]
	v_mfma_f32_16x16x32_bf16 v[102:105], v[146:149], v[192:195], v[102:105]
	v_mfma_f32_16x16x32_bf16 v[102:105], v[166:169], v[196:199], v[102:105]
	v_mfma_f32_16x16x32_bf16 v[98:101], v[170:173], v[192:195], v[98:101]
	v_mfma_f32_16x16x32_bf16 v[98:101], v[180:183], v[196:199], v[98:101]
	v_mfma_f32_16x16x32_bf16 v[86:89], v[146:149], v[200:203], v[86:89]
	v_mfma_f32_16x16x32_bf16 v[86:89], v[166:169], v[204:207], v[86:89]
	v_mfma_f32_16x16x32_bf16 v[82:85], v[170:173], v[200:203], v[82:85]
	v_mfma_f32_16x16x32_bf16 v[82:85], v[180:183], v[204:207], v[82:85]
	v_mfma_f32_16x16x32_bf16 v[70:73], v[146:149], v[208:211], v[70:73]
	v_mfma_f32_16x16x32_bf16 v[70:73], v[166:169], v[212:215], v[70:73]
	v_mfma_f32_16x16x32_bf16 v[66:69], v[170:173], v[208:211], v[66:69]
	v_mfma_f32_16x16x32_bf16 v[66:69], v[180:183], v[212:215], v[66:69]
	s_setprio 0
	s_barrier
	s_add_i32 s28, s50, s31
	s_mov_b32 m0, s28
	ds_read_b128 v[184:187], v178 offset:49152
	ds_read_b128 v[188:191], v178 offset:50176
	ds_read_b128 v[192:195], v178 offset:51200
	ds_read_b128 v[196:199], v178 offset:52224
	ds_read_b128 v[200:203], v178 offset:53248
	ds_read_b128 v[204:207], v178 offset:54272
	ds_read_b128 v[208:211], v178 offset:55296
	ds_read_b128 v[212:215], v178 offset:56320
	s_add_u32 s26, s26, 0x80
	s_addc_u32 s27, s27, 0
	global_load_lds_dwordx4 v152, s[26:27]
	s_add_i32 m0, s28, 0x2000
	s_add_i32 s28, s51, s31
	global_load_lds_dwordx4 v156, s[26:27]
	s_add_u32 s26, s26, 0x2b0000
	s_addc_u32 s27, s27, 0
	s_mov_b32 m0, s28
	s_nop 0
	global_load_lds_dwordx4 v152, s[26:27]
	s_add_i32 m0, s28, 0x2000
	s_nop 0
	global_load_lds_dwordx4 v156, s[26:27]
	s_mov_b32 m0, s38
	s_nop 0
	global_load_lds_dwordx4 v150, s[98:99]
	s_mov_b32 m0, s39
	s_nop 0
	global_load_lds_dwordx4 v154, s[98:99]
	s_waitcnt vmcnt(8)
	s_waitcnt lgkmcnt(0)
	s_barrier
	s_setprio 1
	v_mfma_f32_16x16x32_bf16 v[62:65], v[130:133], v[184:187], v[62:65]
	v_mfma_f32_16x16x32_bf16 v[62:65], v[134:137], v[188:191], v[62:65]
	v_mfma_f32_16x16x32_bf16 v[58:61], v[138:141], v[184:187], v[58:61]
	v_mfma_f32_16x16x32_bf16 v[58:61], v[142:145], v[188:191], v[58:61]
	v_mfma_f32_16x16x32_bf16 v[46:49], v[130:133], v[192:195], v[46:49]
	v_mfma_f32_16x16x32_bf16 v[46:49], v[134:137], v[196:199], v[46:49]
	v_mfma_f32_16x16x32_bf16 v[42:45], v[138:141], v[192:195], v[42:45]
	v_mfma_f32_16x16x32_bf16 v[42:45], v[142:145], v[196:199], v[42:45]
	v_mfma_f32_16x16x32_bf16 v[30:33], v[130:133], v[200:203], v[30:33]
	v_mfma_f32_16x16x32_bf16 v[30:33], v[134:137], v[204:207], v[30:33]
	v_mfma_f32_16x16x32_bf16 v[26:29], v[138:141], v[200:203], v[26:29]
	v_mfma_f32_16x16x32_bf16 v[26:29], v[142:145], v[204:207], v[26:29]
	v_mfma_f32_16x16x32_bf16 v[14:17], v[130:133], v[208:211], v[14:17]
	v_mfma_f32_16x16x32_bf16 v[14:17], v[134:137], v[212:215], v[14:17]
	v_mfma_f32_16x16x32_bf16 v[10:13], v[138:141], v[208:211], v[10:13]
	v_mfma_f32_16x16x32_bf16 v[10:13], v[142:145], v[212:215], v[10:13]
	v_mfma_f32_16x16x32_bf16 v[54:57], v[146:149], v[184:187], v[54:57]
	v_mfma_f32_16x16x32_bf16 v[54:57], v[166:169], v[188:191], v[54:57]
	v_mfma_f32_16x16x32_bf16 v[50:53], v[170:173], v[184:187], v[50:53]
	v_mfma_f32_16x16x32_bf16 v[50:53], v[180:183], v[188:191], v[50:53]
	v_mfma_f32_16x16x32_bf16 v[38:41], v[146:149], v[192:195], v[38:41]
	v_mfma_f32_16x16x32_bf16 v[38:41], v[166:169], v[196:199], v[38:41]
	v_mfma_f32_16x16x32_bf16 v[34:37], v[170:173], v[192:195], v[34:37]
	v_mfma_f32_16x16x32_bf16 v[34:37], v[180:183], v[196:199], v[34:37]
	v_mfma_f32_16x16x32_bf16 v[22:25], v[146:149], v[200:203], v[22:25]
	v_mfma_f32_16x16x32_bf16 v[22:25], v[166:169], v[204:207], v[22:25]
	v_mfma_f32_16x16x32_bf16 v[18:21], v[170:173], v[200:203], v[18:21]
	v_mfma_f32_16x16x32_bf16 v[18:21], v[180:183], v[204:207], v[18:21]
	v_mfma_f32_16x16x32_bf16 v[6:9], v[146:149], v[208:211], v[6:9]
	v_mfma_f32_16x16x32_bf16 v[6:9], v[166:169], v[212:215], v[6:9]
	v_mfma_f32_16x16x32_bf16 v[2:5], v[170:173], v[208:211], v[2:5]
	v_mfma_f32_16x16x32_bf16 v[2:5], v[180:183], v[212:215], v[2:5]
	s_setprio 0
	s_barrier
	s_add_i32 s49, s49, 2
	s_add_u32 s24, s24, 0x100
	s_addc_u32 s25, s25, 0
	s_add_u32 s47, s47, 0x100
	s_addc_u32 s48, s48, 0
	s_cmpk_gt_u32 s49, 0xa9
	s_cbranch_scc0 .LBB0_1325
	s_and_b64 vcc, exec, s[10:11]
	s_cbranch_vccz .LBB0_1328
	s_barrier
